# GEMM loops rewritten: in-wave software pipelining, 1 barrier per super-phase, both wave halves aligned, k-major MFMA passes, counted lgkmcnt, stage loads spread evenly, saddr LDS-DMA
# speedup vs baseline: 1.0002x; 1.0002x over previous
.LBB0_199:
	v_mov_b32_e32 v130, v176
	s_mov_b64 s[0:1], s[94:95]
	s_load_dwordx2 s[0:1], s[0:1], 0xc0
	v_readfirstlane_b32 s23, v130
	v_and_b32_e32 v128, 63, v130
	s_waitcnt lgkmcnt(0)
	v_writelane_b32 v254, s0, 24
	s_nop 1
	v_writelane_b32 v254, s1, 25
	s_mov_b64 s[0:1], s[94:95]
	s_load_dwordx2 s[0:1], s[0:1], 0x68
	s_waitcnt lgkmcnt(0)
	v_writelane_b32 v254, s0, 26
	s_nop 1
	v_writelane_b32 v254, s1, 27
	s_ashr_i32 s0, s23, 6
	v_writelane_b32 v254, s0, 28
	s_cmp_ge_i32 s60, s74
	s_cbranch_scc1 .LBB0_283
	v_readlane_b32 s8, v253, 9
	s_mov_b64 s[4:5], s[94:95]
	s_mov_b64 s[2:3], s[94:95]
	s_mov_b64 s[0:1], s[94:95]
	s_waitcnt vmcnt(0)
	v_mov_b32_e32 v14, v176
	v_readlane_b32 s9, v253, 10
	s_mul_i32 s22, s82, 0x5d00000
	s_and_b64 vcc, exec, s[8:9]
	v_readfirstlane_b32 s6, v14
	s_cbranch_vccz .LBB0_216
	v_lshlrev_b32_e32 v0, 4, v14
	v_add_u32_e32 v1, 0x2000, v0
	v_ashrrev_i32_e32 v2, 31, v1
	v_lshrrev_b32_e32 v2, 22, v2
	v_add_u32_e32 v2, v1, v2
	v_ashrrev_i32_e32 v8, 10, v2
	v_mul_i32_i24_e32 v2, 0x400, v8
	s_load_dwordx2 s[4:5], s[4:5], 0xc0
	s_nop 0
	s_load_dwordx2 s[2:3], s[2:3], 0xc0
	v_sub_u32_e32 v1, v1, v2
	v_lshrrev_b32_e32 v2, 4, v1
	v_bitop3_b32 v1, v2, v1, 32 bitop3:0x6c
	v_ashrrev_i32_e32 v2, 31, v1
	s_waitcnt lgkmcnt(0)
	s_add_u32 s24, s4, 0x17800000
	v_lshrrev_b32_e32 v2, 26, v2
	s_addc_u32 s25, s5, 0
	v_add_u32_e32 v2, v1, v2
	v_lshlrev_b32_e32 v3, 3, v8
	s_add_u32 s2, s2, s22
	v_ashrrev_i32_e32 v9, 6, v2
	v_and_b32_e32 v3, -16, v3
	s_addc_u32 s3, s3, 0
	v_add_u32_e32 v3, v9, v3
	s_add_u32 s26, s2, 0x400000
	v_and_b32_e32 v4, 3, v9
	s_mov_b32 s2, 0xfffe0
	v_lshrrev_b32_e32 v5, 2, v3
	v_lshlrev_b32_e32 v6, 1, v3
	v_and_b32_e32 v2, 0xc0, v2
	v_and_or_b32 v4, v3, s2, v4
	v_and_b32_e32 v5, 4, v5
	v_and_b32_e32 v6, 24, v6
	v_sub_u32_e32 v1, v1, v2
	v_or3_b32 v4, v4, v5, v6
	v_lshlrev_b32_e32 v5, 5, v8
	v_ashrrev_i16_sdwa v1, v177, sext(v1) dst_sel:DWORD dst_unused:UNUSED_PAD src0_sel:DWORD src1_sel:BYTE_0
	v_and_b32_e32 v5, 32, v5
	v_bfe_i32 v10, v1, 0, 16
	v_add_lshl_u32 v1, v5, v10, 1
	v_lshl_add_u32 v132, v4, 12, v1
	v_lshl_add_u32 v134, v3, 12, v1
	v_bfe_i32 v1, v14, 27, 1
	v_lshrrev_b32_e32 v1, 22, v1
	v_add_u32_e32 v1, v0, v1
	v_and_b32_e32 v1, 0xfffffc00, v1
	v_sub_u32_e32 v0, v0, v1
	v_lshrrev_b32_e32 v1, 4, v0
	v_ashrrev_i32_e32 v2, 31, v14
	v_bitop3_b32 v0, v1, v0, 32 bitop3:0x6c
	v_lshrrev_b32_e32 v2, 26, v2
	v_ashrrev_i32_e32 v1, 31, v0
	v_add_u32_e32 v2, v14, v2
	v_lshrrev_b32_e32 v1, 26, v1
	v_ashrrev_i32_e32 v12, 6, v2
	v_add_u32_e32 v1, v0, v1
	v_lshlrev_b32_e32 v2, 3, v12
	v_ashrrev_i32_e32 v11, 6, v1
	v_and_b32_e32 v2, -16, v2
	v_add_u32_e32 v2, v11, v2
	v_and_b32_e32 v3, 3, v11
	v_lshrrev_b32_e32 v4, 2, v2
	v_lshlrev_b32_e32 v5, 1, v2
	v_and_b32_e32 v1, 0xc0, v1
	s_addc_u32 s27, s3, 0
	s_ashr_i32 s7, s6, 6
	v_and_or_b32 v3, v2, s2, v3
	v_and_b32_e32 v4, 4, v4
	v_and_b32_e32 v5, 24, v5
	v_sub_u32_e32 v0, v0, v1
	s_ashr_i32 s8, s6, 8
	s_lshl_b32 s28, s7, 10
	v_or3_b32 v3, v3, v4, v5
	v_lshlrev_b32_e32 v4, 5, v12
	v_ashrrev_i16_sdwa v0, v177, sext(v0) dst_sel:DWORD dst_unused:UNUSED_PAD src0_sel:DWORD src1_sel:BYTE_0
	v_readlane_b32 s2, v253, 28
	v_and_b32_e32 v4, 32, v4
	v_bfe_i32 v13, v0, 0, 16
	v_readlane_b32 s3, v253, 29
	s_add_u32 s18, s26, s2
	v_add_lshl_u32 v0, v4, v13, 1
	s_addc_u32 s19, s27, s3
	s_add_i32 s29, s28, 0x100
	v_lshl_add_u32 v178, v3, 12, v0
	s_add_i32 m0, s29, 0x10000
	v_lshl_add_u32 v136, v2, 12, v0
	global_load_lds_dwordx4 v178, s[18:19]
	s_add_i32 m0, s29, 0x12000
	s_add_u32 s2, s18, 0x80000
	global_load_lds_dwordx4 v132, s[18:19]
	s_addc_u32 s3, s19, 0
	s_add_i32 m0, s29, 0x14000
	s_load_dwordx2 s[0:1], s[0:1], 0xc0
	global_load_lds_dwordx4 v178, s[2:3]
	s_add_i32 m0, s29, 0x16000
	v_mov_b32_e32 v133, v179
	global_load_lds_dwordx4 v132, s[2:3]
	v_readlane_b32 s2, v253, 61
	v_readlane_b32 s3, v253, 62
	s_add_u32 s16, s24, s2
	s_addc_u32 s17, s25, s3
	s_add_i32 s30, s29, 0x2000
	s_mov_b32 m0, s29
	s_add_u32 s2, s16, 0x80000
	global_load_lds_dwordx4 v136, s[16:17]
	s_mov_b32 m0, s30
	s_addc_u32 s3, s17, 0
	s_add_i32 s31, s29, 0x4000
	global_load_lds_dwordx4 v134, s[16:17]
	s_mov_b32 m0, s31
	s_add_i32 s34, s29, 0x6000
	global_load_lds_dwordx4 v136, s[2:3]
	s_mov_b32 m0, s34
	v_mov_b32_e32 v137, v179
	global_load_lds_dwordx4 v134, s[2:3]
	v_mov_b32_e32 v135, v179
	s_cmp_eq_u32 s8, 1
	v_lshl_add_u64 v[6:7], s[18:19], 0, v[178:179]
	v_lshl_add_u64 v[4:5], s[18:19], 0, v[132:133]
	v_lshl_add_u64 v[0:1], s[16:17], 0, v[136:137]
	s_cselect_b64 s[2:3], -1, 0
	s_cmp_lg_u32 s8, 1
	v_lshl_add_u64 v[2:3], s[16:17], 0, v[134:135]
	s_cbranch_scc1 .LBB0_203
	s_nop 0

.LBB0_209:
	ds_read_b128 v[184:187], v147
	v_add_u32_e32 v152, s93, v131
	ds_read_b128 v[142:145], v152 offset:256
	ds_read_b128 v[152:155], v152 offset:2304
	ds_read_b128 v[192:195], v147 offset:2048
	ds_read_b128 v[200:203], v147 offset:4096
	ds_read_b128 v[226:229], v147 offset:6144
	v_add_u32_e32 v168, s62, v131
	ds_read_b128 v[160:163], v168 offset:256
	ds_read_b128 v[168:171], v168 offset:2304
.Lpg_g1_loop:
	s_waitcnt lgkmcnt(6)
	v_mfma_f32_16x16x32_bf16 v[124:127], v[142:145], v[184:187], v[124:127]
	ds_read_b128 v[188:191], v147 offset:1024
	s_add_u32 s18, s16, 0xfff80080
	s_waitcnt lgkmcnt(6)
	v_mfma_f32_16x16x32_bf16 v[120:123], v[152:155], v[184:187], v[120:123]
	v_add_u32_e32 v156, s93, v131
	ds_read_b128 v[148:151], v156 offset:1280
	s_addc_u32 s19, s17, -1
	s_waitcnt lgkmcnt(6)
	v_mfma_f32_16x16x32_bf16 v[116:119], v[142:145], v[192:195], v[116:119]
	ds_read_b128 v[156:159], v156 offset:3328
	s_add_i32 s45, s93, 0x100
	v_mfma_f32_16x16x32_bf16 v[108:111], v[152:155], v[192:195], v[108:111]
	ds_read_b128 v[196:199], v147 offset:3072
	s_cmp_eq_u32 s44, 28
	s_waitcnt lgkmcnt(7)
	v_mfma_f32_16x16x32_bf16 v[100:103], v[142:145], v[200:203], v[100:103]
	ds_read_b128 v[204:207], v147 offset:5120
	s_cselect_b32 s21, s11, s19
	v_mfma_f32_16x16x32_bf16 v[92:95], v[152:155], v[200:203], v[92:95]
	ds_read_b128 v[230:233], v147 offset:7168
	s_cselect_b32 s20, s40, s18
	s_waitcnt lgkmcnt(8)
	v_mfma_f32_16x16x32_bf16 v[84:87], v[142:145], v[226:229], v[84:87]
	v_add_u32_e32 v172, s62, v131
	ds_read_b128 v[164:167], v172 offset:1280
	s_cselect_b32 s19, s9, s43
	v_mfma_f32_16x16x32_bf16 v[76:79], v[152:155], v[226:229], v[76:79]
	ds_read_b128 v[172:175], v172 offset:3328
	s_cselect_b32 s18, s41, s42
	s_waitcnt lgkmcnt(9)
	v_mfma_f32_16x16x32_bf16 v[112:115], v[160:163], v[184:187], v[112:115]
	s_add_i32 s49, s62, 0x100
	s_waitcnt lgkmcnt(8)
	v_mfma_f32_16x16x32_bf16 v[104:107], v[168:171], v[184:187], v[104:107]
	s_add_i32 m0, s29, 0xc000
	v_mfma_f32_16x16x32_bf16 v[96:99], v[160:163], v[192:195], v[96:99]
	s_nop 0
	v_mfma_f32_16x16x32_bf16 v[88:91], v[168:171], v[192:195], v[88:91]
	global_load_lds_dwordx4 v138, s[16:17]
	v_mfma_f32_16x16x32_bf16 v[80:83], v[160:163], v[200:203], v[80:83]
	s_add_i32 m0, s29, 0xe000
	v_mfma_f32_16x16x32_bf16 v[72:75], v[168:171], v[200:203], v[72:75]
	s_nop 0
	v_mfma_f32_16x16x32_bf16 v[68:71], v[160:163], v[226:229], v[68:71]
	global_load_lds_dwordx4 v140, s[16:17]
	v_mfma_f32_16x16x32_bf16 v[64:67], v[168:171], v[226:229], v[64:67]
	s_waitcnt lgkmcnt(0)
	s_waitcnt vmcnt(8)
	s_barrier
	v_mfma_f32_16x16x32_bf16 v[124:127], v[148:151], v[188:191], v[124:127]
	ds_read_b128 v[184:187], v147 offset:16384
	s_add_i32 s45, s45, s28
	v_mfma_f32_16x16x32_bf16 v[120:123], v[156:159], v[188:191], v[120:123]
	ds_read_b128 v[192:195], v147 offset:18432
	v_lshl_add_u64 v[180:181], s[18:19], 0, v[178:179]
	v_mfma_f32_16x16x32_bf16 v[116:119], v[148:151], v[196:199], v[116:119]
	ds_read_b128 v[200:203], v147 offset:20480
	s_mov_b32 m0, s45
	v_mfma_f32_16x16x32_bf16 v[108:111], v[156:159], v[196:199], v[108:111]
	ds_read_b128 v[226:229], v147 offset:22528
	s_nop 0
	v_mfma_f32_16x16x32_bf16 v[100:103], v[148:151], v[204:207], v[100:103]
	global_load_lds_dwordx4 v[180:181], off
	v_mfma_f32_16x16x32_bf16 v[92:95], v[156:159], v[204:207], v[92:95]
	s_add_i32 m0, s45, 0x2000
	v_mfma_f32_16x16x32_bf16 v[84:87], v[148:151], v[230:233], v[84:87]
	s_add_u32 s46, s18, 0x80000
	v_mfma_f32_16x16x32_bf16 v[76:79], v[156:159], v[230:233], v[76:79]
	v_lshl_add_u64 v[182:183], s[18:19], 0, v[132:133]
	v_mfma_f32_16x16x32_bf16 v[112:115], v[164:167], v[188:191], v[112:115]
	s_addc_u32 s47, s19, 0
	v_mfma_f32_16x16x32_bf16 v[104:107], v[172:175], v[188:191], v[104:107]
	s_add_i32 s45, s49, s28
	v_mfma_f32_16x16x32_bf16 v[96:99], v[164:167], v[196:199], v[96:99]
	global_load_lds_dwordx4 v[182:183], off
	v_mfma_f32_16x16x32_bf16 v[88:91], v[172:175], v[196:199], v[88:91]
	s_mov_b32 m0, s45
	v_mfma_f32_16x16x32_bf16 v[80:83], v[164:167], v[204:207], v[80:83]
	v_lshl_add_u64 v[210:211], s[20:21], 0, v[134:135]
	v_mfma_f32_16x16x32_bf16 v[72:75], v[172:175], v[204:207], v[72:75]
	global_load_lds_dwordx4 v178, s[46:47]
	v_mfma_f32_16x16x32_bf16 v[68:71], v[164:167], v[230:233], v[68:71]
	s_add_i32 m0, s45, 0x2000
	v_mfma_f32_16x16x32_bf16 v[64:67], v[172:175], v[230:233], v[64:67]
	s_nop 0
	s_waitcnt lgkmcnt(3)
	v_mfma_f32_16x16x32_bf16 v[60:63], v[142:145], v[184:187], v[60:63]
	ds_read_b128 v[188:191], v147 offset:17408
	global_load_lds_dwordx4 v132, s[46:47]
	v_mfma_f32_16x16x32_bf16 v[56:59], v[152:155], v[184:187], v[56:59]
	ds_read_b128 v[196:199], v147 offset:19456
	s_waitcnt lgkmcnt(4)
	v_mfma_f32_16x16x32_bf16 v[52:55], v[142:145], v[192:195], v[52:55]
	ds_read_b128 v[204:207], v147 offset:21504
	v_mfma_f32_16x16x32_bf16 v[44:47], v[152:155], v[192:195], v[44:47]
	ds_read_b128 v[230:233], v147 offset:23552
	s_waitcnt lgkmcnt(5)
	v_mfma_f32_16x16x32_bf16 v[36:39], v[142:145], v[200:203], v[36:39]
	v_mfma_f32_16x16x32_bf16 v[28:31], v[152:155], v[200:203], v[28:31]
	s_waitcnt lgkmcnt(4)
	v_mfma_f32_16x16x32_bf16 v[20:23], v[142:145], v[226:229], v[20:23]
	v_mfma_f32_16x16x32_bf16 v[12:15], v[152:155], v[226:229], v[12:15]
	v_mfma_f32_16x16x32_bf16 v[48:51], v[160:163], v[184:187], v[48:51]
	v_mfma_f32_16x16x32_bf16 v[40:43], v[168:171], v[184:187], v[40:43]
	v_mfma_f32_16x16x32_bf16 v[32:35], v[160:163], v[192:195], v[32:35]
	v_mfma_f32_16x16x32_bf16 v[24:27], v[168:171], v[192:195], v[24:27]
	v_mfma_f32_16x16x32_bf16 v[16:19], v[160:163], v[200:203], v[16:19]
	v_mfma_f32_16x16x32_bf16 v[8:11], v[168:171], v[200:203], v[8:11]
	v_mfma_f32_16x16x32_bf16 v[4:7], v[160:163], v[226:229], v[4:7]
	v_mfma_f32_16x16x32_bf16 v[0:3], v[168:171], v[226:229], v[0:3]
	s_waitcnt lgkmcnt(0)
	s_waitcnt vmcnt(6)
	s_barrier
	v_mfma_f32_16x16x32_bf16 v[60:63], v[148:151], v[188:191], v[60:63]
	ds_read_b128 v[184:187], v147 offset:32768
	v_lshl_add_u64 v[208:209], s[20:21], 0, v[136:137]
	v_mfma_f32_16x16x32_bf16 v[56:59], v[156:159], v[188:191], v[56:59]
	v_add_u32_e32 v152, s63, v131
	ds_read_b128 v[142:145], v152 offset:256
	s_mov_b32 m0, s29
	v_mfma_f32_16x16x32_bf16 v[52:55], v[148:151], v[196:199], v[52:55]
	ds_read_b128 v[152:155], v152 offset:2304
	s_nop 0
	v_mfma_f32_16x16x32_bf16 v[44:47], v[156:159], v[196:199], v[44:47]
	ds_read_b128 v[192:195], v147 offset:34816
	global_load_lds_dwordx4 v[208:209], off
	v_mfma_f32_16x16x32_bf16 v[36:39], v[148:151], v[204:207], v[36:39]
	ds_read_b128 v[200:203], v147 offset:36864
	s_mov_b32 m0, s30
	v_mfma_f32_16x16x32_bf16 v[28:31], v[156:159], v[204:207], v[28:31]
	ds_read_b128 v[226:229], v147 offset:38912
	s_nop 0
	v_mfma_f32_16x16x32_bf16 v[20:23], v[148:151], v[230:233], v[20:23]
	v_add_u32_e32 v168, s75, v131
	ds_read_b128 v[160:163], v168 offset:256
	global_load_lds_dwordx4 v[210:211], off
	v_mfma_f32_16x16x32_bf16 v[12:15], v[156:159], v[230:233], v[12:15]
	ds_read_b128 v[168:171], v168 offset:2304
	s_add_i32 s45, s63, 0x100
	v_mfma_f32_16x16x32_bf16 v[48:51], v[164:167], v[188:191], v[48:51]
	s_add_i32 s46, s75, 0x100
	v_mfma_f32_16x16x32_bf16 v[40:43], v[172:175], v[188:191], v[40:43]
	s_add_u32 s20, s20, 0x80000
	v_mfma_f32_16x16x32_bf16 v[32:35], v[164:167], v[196:199], v[32:35]
	s_addc_u32 s21, s21, 0
	v_mfma_f32_16x16x32_bf16 v[24:27], v[172:175], v[196:199], v[24:27]
	s_mov_b32 m0, s31
	v_mfma_f32_16x16x32_bf16 v[16:19], v[164:167], v[204:207], v[16:19]
	s_nop 0
	v_mfma_f32_16x16x32_bf16 v[8:11], v[172:175], v[204:207], v[8:11]
	global_load_lds_dwordx4 v136, s[20:21]
	v_mfma_f32_16x16x32_bf16 v[4:7], v[164:167], v[230:233], v[4:7]
	s_mov_b32 m0, s34
	v_mfma_f32_16x16x32_bf16 v[0:3], v[172:175], v[230:233], v[0:3]
	s_nop 0
	s_waitcnt lgkmcnt(6)
	v_mfma_f32_16x16x32_bf16 v[124:127], v[142:145], v[184:187], v[124:127]
	ds_read_b128 v[188:191], v147 offset:33792
	global_load_lds_dwordx4 v134, s[20:21]
	s_waitcnt lgkmcnt(6)
	v_mfma_f32_16x16x32_bf16 v[120:123], v[152:155], v[184:187], v[120:123]
	v_add_u32_e32 v156, s63, v131
	ds_read_b128 v[148:151], v156 offset:1280
	s_waitcnt lgkmcnt(6)
	v_mfma_f32_16x16x32_bf16 v[116:119], v[142:145], v[192:195], v[116:119]
	ds_read_b128 v[156:159], v156 offset:3328
	v_mfma_f32_16x16x32_bf16 v[108:111], v[152:155], v[192:195], v[108:111]
	ds_read_b128 v[196:199], v147 offset:35840
	s_waitcnt lgkmcnt(7)
	v_mfma_f32_16x16x32_bf16 v[100:103], v[142:145], v[200:203], v[100:103]
	ds_read_b128 v[204:207], v147 offset:37888
	v_mfma_f32_16x16x32_bf16 v[92:95], v[152:155], v[200:203], v[92:95]
	ds_read_b128 v[230:233], v147 offset:39936
	s_waitcnt lgkmcnt(8)
	v_mfma_f32_16x16x32_bf16 v[84:87], v[142:145], v[226:229], v[84:87]
	v_add_u32_e32 v172, s75, v131
	ds_read_b128 v[164:167], v172 offset:1280
	v_mfma_f32_16x16x32_bf16 v[76:79], v[152:155], v[226:229], v[76:79]
	ds_read_b128 v[172:175], v172 offset:3328
	s_waitcnt lgkmcnt(9)
	v_mfma_f32_16x16x32_bf16 v[112:115], v[160:163], v[184:187], v[112:115]
	s_waitcnt lgkmcnt(8)
	v_mfma_f32_16x16x32_bf16 v[104:107], v[168:171], v[184:187], v[104:107]
	v_mfma_f32_16x16x32_bf16 v[96:99], v[160:163], v[192:195], v[96:99]
	v_mfma_f32_16x16x32_bf16 v[88:91], v[168:171], v[192:195], v[88:91]
	v_mfma_f32_16x16x32_bf16 v[80:83], v[160:163], v[200:203], v[80:83]
	v_mfma_f32_16x16x32_bf16 v[72:75], v[168:171], v[200:203], v[72:75]
	v_mfma_f32_16x16x32_bf16 v[68:71], v[160:163], v[226:229], v[68:71]
	v_mfma_f32_16x16x32_bf16 v[64:67], v[168:171], v[226:229], v[64:67]
	s_waitcnt lgkmcnt(0)
	s_waitcnt vmcnt(8)
	s_barrier
	v_mfma_f32_16x16x32_bf16 v[124:127], v[148:151], v[188:191], v[124:127]
	ds_read_b128 v[184:187], v147 offset:49152
	s_add_i32 s20, s45, s28
	v_mfma_f32_16x16x32_bf16 v[120:123], v[156:159], v[188:191], v[120:123]
	ds_read_b128 v[192:195], v147 offset:51200
	v_lshl_add_u64 v[180:181], v[180:181], 0, s[78:79]
	v_mfma_f32_16x16x32_bf16 v[116:119], v[148:151], v[196:199], v[116:119]
	ds_read_b128 v[200:203], v147 offset:53248
	s_mov_b32 m0, s20
	v_mfma_f32_16x16x32_bf16 v[108:111], v[156:159], v[196:199], v[108:111]
	ds_read_b128 v[226:229], v147 offset:55296
	s_nop 0
	v_mfma_f32_16x16x32_bf16 v[100:103], v[148:151], v[204:207], v[100:103]
	global_load_lds_dwordx4 v[180:181], off
	v_mfma_f32_16x16x32_bf16 v[92:95], v[156:159], v[204:207], v[92:95]
	s_add_i32 m0, s20, 0x2000
	v_mfma_f32_16x16x32_bf16 v[84:87], v[148:151], v[230:233], v[84:87]
	s_add_u32 s18, s18, 0x80080
	v_mfma_f32_16x16x32_bf16 v[76:79], v[156:159], v[230:233], v[76:79]
	v_lshl_add_u64 v[180:181], v[182:183], 0, s[78:79]
	v_mfma_f32_16x16x32_bf16 v[112:115], v[164:167], v[188:191], v[112:115]
	s_addc_u32 s19, s19, 0
	v_mfma_f32_16x16x32_bf16 v[104:107], v[172:175], v[188:191], v[104:107]
	s_add_i32 s20, s46, s28
	v_mfma_f32_16x16x32_bf16 v[96:99], v[164:167], v[196:199], v[96:99]
	global_load_lds_dwordx4 v[180:181], off
	v_mfma_f32_16x16x32_bf16 v[88:91], v[172:175], v[196:199], v[88:91]
	s_mov_b32 m0, s20
	v_mfma_f32_16x16x32_bf16 v[80:83], v[164:167], v[204:207], v[80:83]
	s_nop 0
	v_mfma_f32_16x16x32_bf16 v[72:75], v[172:175], v[204:207], v[72:75]
	global_load_lds_dwordx4 v178, s[18:19]
	v_mfma_f32_16x16x32_bf16 v[68:71], v[164:167], v[230:233], v[68:71]
	s_add_i32 m0, s20, 0x2000
	v_mfma_f32_16x16x32_bf16 v[64:67], v[172:175], v[230:233], v[64:67]
	s_nop 0
	s_waitcnt lgkmcnt(3)
	v_mfma_f32_16x16x32_bf16 v[60:63], v[142:145], v[184:187], v[60:63]
	ds_read_b128 v[188:191], v147 offset:50176
	global_load_lds_dwordx4 v132, s[18:19]
	v_mfma_f32_16x16x32_bf16 v[56:59], v[152:155], v[184:187], v[56:59]
	ds_read_b128 v[196:199], v147 offset:52224
	s_waitcnt lgkmcnt(4)
	v_mfma_f32_16x16x32_bf16 v[52:55], v[142:145], v[192:195], v[52:55]
	ds_read_b128 v[204:207], v147 offset:54272
	v_mfma_f32_16x16x32_bf16 v[44:47], v[152:155], v[192:195], v[44:47]
	ds_read_b128 v[230:233], v147 offset:56320
	s_waitcnt lgkmcnt(5)
	v_mfma_f32_16x16x32_bf16 v[36:39], v[142:145], v[200:203], v[36:39]
	v_mfma_f32_16x16x32_bf16 v[28:31], v[152:155], v[200:203], v[28:31]
	s_waitcnt lgkmcnt(4)
	v_mfma_f32_16x16x32_bf16 v[20:23], v[142:145], v[226:229], v[20:23]
	v_mfma_f32_16x16x32_bf16 v[12:15], v[152:155], v[226:229], v[12:15]
	v_mfma_f32_16x16x32_bf16 v[48:51], v[160:163], v[184:187], v[48:51]
	v_mfma_f32_16x16x32_bf16 v[40:43], v[168:171], v[184:187], v[40:43]
	v_mfma_f32_16x16x32_bf16 v[32:35], v[160:163], v[192:195], v[32:35]
	v_mfma_f32_16x16x32_bf16 v[24:27], v[168:171], v[192:195], v[24:27]
	v_mfma_f32_16x16x32_bf16 v[16:19], v[160:163], v[200:203], v[16:19]
	v_mfma_f32_16x16x32_bf16 v[8:11], v[168:171], v[200:203], v[8:11]
	v_mfma_f32_16x16x32_bf16 v[4:7], v[160:163], v[226:229], v[4:7]
	v_mfma_f32_16x16x32_bf16 v[0:3], v[168:171], v[226:229], v[0:3]
	s_waitcnt lgkmcnt(0)
	s_waitcnt vmcnt(6)
	s_barrier
	v_mfma_f32_16x16x32_bf16 v[60:63], v[148:151], v[188:191], v[60:63]
	ds_read_b128 v[184:187], v147
	v_lshl_add_u64 v[180:181], v[208:209], 0, s[78:79]
	v_mfma_f32_16x16x32_bf16 v[56:59], v[156:159], v[188:191], v[56:59]
	v_add_u32_e32 v152, s93, v131
	ds_read_b128 v[142:145], v152 offset:256
	s_mov_b32 m0, s35
	v_mfma_f32_16x16x32_bf16 v[52:55], v[148:151], v[196:199], v[52:55]
	ds_read_b128 v[152:155], v152 offset:2304
	s_nop 0
	v_mfma_f32_16x16x32_bf16 v[44:47], v[156:159], v[196:199], v[44:47]
	ds_read_b128 v[192:195], v147 offset:2048
	global_load_lds_dwordx4 v[180:181], off
	v_mfma_f32_16x16x32_bf16 v[36:39], v[148:151], v[204:207], v[36:39]
	ds_read_b128 v[200:203], v147 offset:4096
	v_lshl_add_u64 v[180:181], v[210:211], 0, s[78:79]
	v_mfma_f32_16x16x32_bf16 v[28:31], v[156:159], v[204:207], v[28:31]
	ds_read_b128 v[226:229], v147 offset:6144
	s_mov_b32 m0, s36
	v_mfma_f32_16x16x32_bf16 v[20:23], v[148:151], v[230:233], v[20:23]
	v_add_u32_e32 v168, s62, v131
	ds_read_b128 v[160:163], v168 offset:256
	s_nop 0
	v_mfma_f32_16x16x32_bf16 v[12:15], v[156:159], v[230:233], v[12:15]
	ds_read_b128 v[168:171], v168 offset:2304
	global_load_lds_dwordx4 v[180:181], off
	v_mfma_f32_16x16x32_bf16 v[48:51], v[164:167], v[188:191], v[48:51]
	v_mfma_f32_16x16x32_bf16 v[40:43], v[172:175], v[188:191], v[40:43]
	v_mfma_f32_16x16x32_bf16 v[32:35], v[164:167], v[196:199], v[32:35]
	v_mfma_f32_16x16x32_bf16 v[24:27], v[172:175], v[196:199], v[24:27]
	v_mfma_f32_16x16x32_bf16 v[16:19], v[164:167], v[204:207], v[16:19]
	v_mfma_f32_16x16x32_bf16 v[8:11], v[172:175], v[204:207], v[8:11]
	v_mfma_f32_16x16x32_bf16 v[4:7], v[164:167], v[230:233], v[4:7]
	v_mfma_f32_16x16x32_bf16 v[0:3], v[172:175], v[230:233], v[0:3]
	s_add_i32 s44, s44, 2
	s_add_u32 s16, s16, 0x100
	s_addc_u32 s17, s17, 0
	s_add_u32 s42, s42, 0x100
	s_addc_u32 s43, s43, 0
	s_cmp_gt_u32 s44, 29
	s_cbranch_scc0 .Lpg_g1_loop
	s_waitcnt lgkmcnt(0)
	s_and_b64 vcc, exec, s[6:7]
	s_cbranch_vccz .LBB0_212
	s_nop 0
.LBB0_212:
	v_lshl_or_b32 v144, s38, 8, v146
	v_lshl_add_u32 v150, s39, 8, v129
	v_ashrrev_i32_e32 v145, 31, v144
	v_mov_b64_e32 v[142:143], s[4:5]
	v_mad_i64_i32 v[148:149], s[16:17], v150, s91, v[142:143]
	v_lshlrev_b64 v[144:145], 1, v[144:145]
	v_lshl_add_u64 v[148:149], v[148:149], 0, v[144:145]
	v_cvt_pk_bf16_f32 v124, v124, v125
	v_cvt_pk_bf16_f32 v125, v126, v127
	v_cvt_pk_bf16_f32 v126, v120, v121
	v_cvt_pk_bf16_f32 v127, v122, v123
	global_store_dwordx4 v[148:149], v[124:127], off
	v_cvt_pk_bf16_f32 v112, v112, v113
	v_cvt_pk_bf16_f32 v113, v114, v115
	v_cvt_pk_bf16_f32 v114, v104, v105
	v_or_b32_e32 v104, 16, v150
	v_mad_i64_i32 v[104:105], s[16:17], v104, s91, v[142:143]
	v_cvt_pk_bf16_f32 v115, v106, v107
	global_store_dwordx4 v[148:149], v[112:115], off offset:256
	s_andn2_b64 vcc, exec, s[0:1]
	s_mov_b64 s[0:1], -1
	v_lshl_add_u64 v[112:113], v[104:105], 0, v[144:145]
	v_cvt_pk_bf16_f32 v104, v116, v117
	v_cvt_pk_bf16_f32 v105, v118, v119
	v_cvt_pk_bf16_f32 v106, v108, v109
	v_cvt_pk_bf16_f32 v107, v110, v111
	global_store_dwordx4 v[112:113], v[104:107], off
	v_cvt_pk_bf16_f32 v96, v96, v97
	v_cvt_pk_bf16_f32 v97, v98, v99
	v_cvt_pk_bf16_f32 v98, v88, v89
	v_or_b32_e32 v88, 32, v150
	v_mad_i64_i32 v[88:89], s[16:17], v88, s91, v[142:143]
	v_cvt_pk_bf16_f32 v99, v90, v91
	global_store_dwordx4 v[112:113], v[96:99], off offset:256
	s_nop 1
	v_lshl_add_u64 v[96:97], v[88:89], 0, v[144:145]
	v_cvt_pk_bf16_f32 v88, v100, v101
	v_cvt_pk_bf16_f32 v89, v102, v103
	v_cvt_pk_bf16_f32 v90, v92, v93
	v_cvt_pk_bf16_f32 v91, v94, v95
	global_store_dwordx4 v[96:97], v[88:91], off
	v_cvt_pk_bf16_f32 v80, v80, v81
	v_cvt_pk_bf16_f32 v81, v82, v83
	v_cvt_pk_bf16_f32 v82, v72, v73
	v_or_b32_e32 v72, 48, v150
	v_mad_i64_i32 v[72:73], s[16:17], v72, s91, v[142:143]
	v_cvt_pk_bf16_f32 v83, v74, v75
	global_store_dwordx4 v[96:97], v[80:83], off offset:256
	s_nop 1
	v_lshl_add_u64 v[80:81], v[72:73], 0, v[144:145]
	v_cvt_pk_bf16_f32 v72, v84, v85
	v_cvt_pk_bf16_f32 v73, v86, v87
	v_cvt_pk_bf16_f32 v74, v76, v77
	v_cvt_pk_bf16_f32 v75, v78, v79
	global_store_dwordx4 v[80:81], v[72:75], off
	v_cvt_pk_bf16_f32 v68, v68, v69
	v_cvt_pk_bf16_f32 v69, v70, v71
	v_cvt_pk_bf16_f32 v70, v64, v65
	v_add_u32_e32 v64, 0x80, v150
	v_mad_i64_i32 v[64:65], s[16:17], v64, s91, v[142:143]
	v_lshl_add_u64 v[64:65], v[64:65], 0, v[144:145]
	v_cvt_pk_bf16_f32 v71, v66, v67
	global_store_dwordx4 v[80:81], v[68:71], off offset:256
	v_cvt_pk_bf16_f32 v60, v60, v61
	v_cvt_pk_bf16_f32 v61, v62, v63
	v_cvt_pk_bf16_f32 v62, v56, v57
	v_cvt_pk_bf16_f32 v63, v58, v59
	global_store_dwordx4 v[64:65], v[60:63], off
	v_cvt_pk_bf16_f32 v48, v48, v49
	v_cvt_pk_bf16_f32 v49, v50, v51
	v_cvt_pk_bf16_f32 v50, v40, v41
	v_add_u32_e32 v40, 0x90, v150
	v_mad_i64_i32 v[40:41], s[16:17], v40, s91, v[142:143]
	v_cvt_pk_bf16_f32 v51, v42, v43
	global_store_dwordx4 v[64:65], v[48:51], off offset:256
	s_nop 1
	v_lshl_add_u64 v[48:49], v[40:41], 0, v[144:145]
	v_cvt_pk_bf16_f32 v40, v52, v53
	v_cvt_pk_bf16_f32 v41, v54, v55
	v_cvt_pk_bf16_f32 v42, v44, v45
	v_cvt_pk_bf16_f32 v43, v46, v47
	global_store_dwordx4 v[48:49], v[40:43], off
	v_cvt_pk_bf16_f32 v32, v32, v33
	v_cvt_pk_bf16_f32 v33, v34, v35
	v_cvt_pk_bf16_f32 v34, v24, v25
	v_add_u32_e32 v24, 0xa0, v150
	v_mad_i64_i32 v[24:25], s[16:17], v24, s91, v[142:143]
	v_cvt_pk_bf16_f32 v35, v26, v27
	global_store_dwordx4 v[48:49], v[32:35], off offset:256
	s_nop 1
	v_lshl_add_u64 v[32:33], v[24:25], 0, v[144:145]
	v_cvt_pk_bf16_f32 v24, v36, v37
	v_cvt_pk_bf16_f32 v25, v38, v39
	v_cvt_pk_bf16_f32 v26, v28, v29
	v_cvt_pk_bf16_f32 v27, v30, v31
	global_store_dwordx4 v[32:33], v[24:27], off
	v_cvt_pk_bf16_f32 v16, v16, v17
	v_cvt_pk_bf16_f32 v17, v18, v19
	v_cvt_pk_bf16_f32 v18, v8, v9
	v_add_u32_e32 v8, 0xb0, v150
	v_mad_i64_i32 v[8:9], s[16:17], v8, s91, v[142:143]
	v_cvt_pk_bf16_f32 v19, v10, v11
	global_store_dwordx4 v[32:33], v[16:19], off offset:256
	s_nop 1
	v_lshl_add_u64 v[16:17], v[8:9], 0, v[144:145]
	v_cvt_pk_bf16_f32 v8, v20, v21
	v_cvt_pk_bf16_f32 v9, v22, v23
	v_cvt_pk_bf16_f32 v10, v12, v13
	v_cvt_pk_bf16_f32 v11, v14, v15
	global_store_dwordx4 v[16:17], v[8:11], off
	v_cvt_pk_bf16_f32 v4, v4, v5
	v_cvt_pk_bf16_f32 v5, v6, v7
	v_cvt_pk_bf16_f32 v6, v0, v1
	v_cvt_pk_bf16_f32 v7, v2, v3
	global_store_dwordx4 v[16:17], v[4:7], off offset:256
	s_cbranch_vccnz .LBB0_205
	s_andn2_b64 vcc, exec, s[2:3]
	s_cbranch_vccnz .LBB0_204
	s_nop 0
	s_branch .LBB0_204

.LBB0_820:
	s_add_i32 s0, s60, 4
	s_cmp_ge_i32 s0, s74
	v_readlane_b32 s0, v253, 19
	v_readlane_b32 s1, v253, 20
	s_waitcnt vmcnt(0)
	s_nop 0
	v_cndmask_b32_e64 v0, 0, 1, s[0:1]
	v_cmp_ne_u32_e64 s[8:9], 1, v0
	s_cbranch_scc1 .LBB0_915
	s_mov_b64 s[4:5], s[94:95]
	s_mov_b64 s[2:3], s[94:95]
	s_mov_b64 s[0:1], s[94:95]
	s_waitcnt vmcnt(40)
	v_mov_b32_e32 v14, v176
	s_and_b64 vcc, exec, s[8:9]
	v_readfirstlane_b32 s6, v14
	s_cbranch_vccnz .LBB0_841
	v_lshlrev_b32_e32 v0, 4, v14
	v_add_u32_e32 v1, 0x2000, v0
	v_ashrrev_i32_e32 v2, 31, v1
	v_lshrrev_b32_e32 v2, 22, v2
	v_add_u32_e32 v2, v1, v2
	v_ashrrev_i32_e32 v8, 10, v2
	v_mul_i32_i24_e32 v2, 0x400, v8
	s_load_dwordx2 s[4:5], s[4:5], 0xc0
	s_nop 0
	s_load_dwordx2 s[2:3], s[2:3], 0xc0
	v_sub_u32_e32 v1, v1, v2
	v_lshrrev_b32_e32 v2, 4, v1
	v_bitop3_b32 v1, v2, v1, 32 bitop3:0x6c
	v_ashrrev_i32_e32 v2, 31, v1
	s_waitcnt lgkmcnt(0)
	s_add_u32 s24, s4, 0x29200000
	v_lshrrev_b32_e32 v2, 26, v2
	s_mul_i32 s7, s82, 0x5d00000
	s_addc_u32 s25, s5, 0
	v_add_u32_e32 v2, v1, v2
	v_lshlrev_b32_e32 v3, 3, v8
	s_add_u32 s2, s2, s7
	v_ashrrev_i32_e32 v9, 6, v2
	v_and_b32_e32 v3, -16, v3
	s_addc_u32 s3, s3, 0
	v_add_u32_e32 v3, v9, v3
	s_add_u32 s26, s2, 0x1900000
	v_and_b32_e32 v4, 3, v9
	s_mov_b32 s2, 0xfffe0
	v_lshrrev_b32_e32 v5, 2, v3
	v_lshlrev_b32_e32 v6, 1, v3
	v_and_b32_e32 v2, 0xc0, v2
	v_and_or_b32 v4, v3, s2, v4
	v_and_b32_e32 v5, 4, v5
	v_and_b32_e32 v6, 24, v6
	v_sub_u32_e32 v1, v1, v2
	v_or3_b32 v4, v4, v5, v6
	v_lshlrev_b32_e32 v5, 5, v8
	v_ashrrev_i16_sdwa v1, v177, sext(v1) dst_sel:DWORD dst_unused:UNUSED_PAD src0_sel:DWORD src1_sel:BYTE_0
	v_and_b32_e32 v5, 32, v5
	v_bfe_i32 v10, v1, 0, 16
	v_add_lshl_u32 v1, v5, v10, 1
	v_lshl_add_u32 v130, v4, 12, v1
	v_lshl_add_u32 v132, v3, 12, v1
	v_bfe_i32 v1, v14, 27, 1
	v_lshrrev_b32_e32 v1, 22, v1
	v_add_u32_e32 v1, v0, v1
	v_and_b32_e32 v1, 0xfffffc00, v1
	v_sub_u32_e32 v0, v0, v1
	v_lshrrev_b32_e32 v1, 4, v0
	v_ashrrev_i32_e32 v2, 31, v14
	v_bitop3_b32 v0, v1, v0, 32 bitop3:0x6c
	v_lshrrev_b32_e32 v2, 26, v2
	v_ashrrev_i32_e32 v1, 31, v0
	v_add_u32_e32 v2, v14, v2
	v_lshrrev_b32_e32 v1, 26, v1
	v_ashrrev_i32_e32 v12, 6, v2
	v_add_u32_e32 v1, v0, v1
	v_lshlrev_b32_e32 v2, 3, v12
	v_ashrrev_i32_e32 v11, 6, v1
	v_and_b32_e32 v2, -16, v2
	v_add_u32_e32 v2, v11, v2
	v_and_b32_e32 v3, 3, v11
	v_lshrrev_b32_e32 v4, 2, v2
	v_lshlrev_b32_e32 v5, 1, v2
	v_and_b32_e32 v1, 0xc0, v1
	s_addc_u32 s27, s3, 0
	s_ashr_i32 s7, s6, 6
	v_and_or_b32 v3, v2, s2, v3
	v_and_b32_e32 v4, 4, v4
	v_and_b32_e32 v5, 24, v5
	v_sub_u32_e32 v0, v0, v1
	s_ashr_i32 s10, s6, 8
	s_lshl_b32 s28, s7, 10
	v_or3_b32 v3, v3, v4, v5
	v_lshlrev_b32_e32 v4, 5, v12
	v_ashrrev_i16_sdwa v0, v177, sext(v0) dst_sel:DWORD dst_unused:UNUSED_PAD src0_sel:DWORD src1_sel:BYTE_0
	v_readlane_b32 s2, v253, 31
	v_and_b32_e32 v4, 32, v4
	v_bfe_i32 v13, v0, 0, 16
	v_readlane_b32 s3, v253, 32
	s_add_u32 s20, s26, s2
	v_add_lshl_u32 v0, v4, v13, 1
	s_addc_u32 s21, s27, s3
	s_add_i32 s29, s28, 0x100
	v_lshl_add_u32 v178, v3, 12, v0
	s_add_i32 m0, s29, 0x10000
	v_lshl_add_u32 v134, v2, 12, v0
	global_load_lds_dwordx4 v178, s[20:21]
	s_add_i32 m0, s29, 0x12000
	s_add_u32 s2, s20, 0x80000
	global_load_lds_dwordx4 v130, s[20:21]
	s_addc_u32 s3, s21, 0
	s_add_i32 m0, s29, 0x14000
	s_load_dwordx2 s[0:1], s[0:1], 0xc0
	global_load_lds_dwordx4 v178, s[2:3]
	s_add_i32 m0, s29, 0x16000
	v_mov_b32_e32 v131, v179
	global_load_lds_dwordx4 v130, s[2:3]
	v_readlane_b32 s2, v253, 63
	v_readlane_b32 s3, v254, 0
	s_add_u32 s18, s24, s2
	s_addc_u32 s19, s25, s3
	s_add_i32 s30, s29, 0x2000
	s_mov_b32 m0, s29
	s_add_u32 s2, s18, 0x80000
	global_load_lds_dwordx4 v134, s[18:19]
	s_mov_b32 m0, s30
	s_addc_u32 s3, s19, 0
	s_add_i32 s31, s29, 0x4000
	global_load_lds_dwordx4 v132, s[18:19]
	s_mov_b32 m0, s31
	s_add_i32 s34, s29, 0x6000
	global_load_lds_dwordx4 v134, s[2:3]
	s_mov_b32 m0, s34
	v_mov_b32_e32 v135, v179
	global_load_lds_dwordx4 v132, s[2:3]
	v_mov_b32_e32 v133, v179
	s_cmp_eq_u32 s10, 1
	v_lshl_add_u64 v[6:7], s[20:21], 0, v[178:179]
	v_lshl_add_u64 v[4:5], s[20:21], 0, v[130:131]
	v_lshl_add_u64 v[0:1], s[18:19], 0, v[134:135]
	s_cselect_b64 s[2:3], -1, 0
	s_cmp_lg_u32 s10, 1
	v_lshl_add_u64 v[2:3], s[18:19], 0, v[132:133]
	s_cbranch_scc1 .LBB0_824
	s_nop 0

.LBB0_834:
	ds_read_b128 v[184:187], v144
	v_add_u32_e32 v154, s93, v142
	ds_read_b128 v[146:149], v154 offset:256
	ds_read_b128 v[154:157], v154 offset:2304
	ds_read_b128 v[192:195], v144 offset:2048
	ds_read_b128 v[200:203], v144 offset:4096
	ds_read_b128 v[208:211], v144 offset:6144
	v_add_u32_e32 v170, s62, v142
	ds_read_b128 v[162:165], v170 offset:256
	ds_read_b128 v[170:173], v170 offset:2304
.Lpg_g7_loop:
	s_waitcnt lgkmcnt(6)
	v_mfma_f32_16x16x32_bf16 v[124:127], v[146:149], v[184:187], v[124:127]
	ds_read_b128 v[188:191], v144 offset:1024
	s_add_u32 s20, s18, 0xfff80080
	s_waitcnt lgkmcnt(6)
	v_mfma_f32_16x16x32_bf16 v[120:123], v[154:157], v[184:187], v[120:123]
	v_add_u32_e32 v158, s93, v142
	ds_read_b128 v[150:153], v158 offset:1280
	s_addc_u32 s21, s19, -1
	s_waitcnt lgkmcnt(6)
	v_mfma_f32_16x16x32_bf16 v[116:119], v[146:149], v[192:195], v[116:119]
	ds_read_b128 v[158:161], v158 offset:3328
	s_add_i32 s45, s93, 0x100
	v_mfma_f32_16x16x32_bf16 v[108:111], v[154:157], v[192:195], v[108:111]
	ds_read_b128 v[196:199], v144 offset:3072
	s_cmp_eq_u32 s44, 28
	s_waitcnt lgkmcnt(7)
	v_mfma_f32_16x16x32_bf16 v[100:103], v[146:149], v[200:203], v[100:103]
	ds_read_b128 v[204:207], v144 offset:5120
	s_cselect_b32 s23, s13, s21
	v_mfma_f32_16x16x32_bf16 v[92:95], v[154:157], v[200:203], v[92:95]
	ds_read_b128 v[226:229], v144 offset:7168
	s_cselect_b32 s22, s40, s20
	s_waitcnt lgkmcnt(8)
	v_mfma_f32_16x16x32_bf16 v[84:87], v[146:149], v[208:211], v[84:87]
	v_add_u32_e32 v180, s62, v142
	ds_read_b128 v[166:169], v180 offset:1280
	s_cselect_b32 s21, s11, s43
	v_mfma_f32_16x16x32_bf16 v[76:79], v[154:157], v[208:211], v[76:79]
	ds_read_b128 v[180:183], v180 offset:3328
	s_cselect_b32 s20, s41, s42
	s_waitcnt lgkmcnt(9)
	v_mfma_f32_16x16x32_bf16 v[112:115], v[162:165], v[184:187], v[112:115]
	s_add_i32 s49, s62, 0x100
	s_waitcnt lgkmcnt(8)
	v_mfma_f32_16x16x32_bf16 v[104:107], v[170:173], v[184:187], v[104:107]
	s_add_i32 m0, s29, 0xc000
	v_mfma_f32_16x16x32_bf16 v[96:99], v[162:165], v[192:195], v[96:99]
	s_nop 0
	v_mfma_f32_16x16x32_bf16 v[88:91], v[170:173], v[192:195], v[88:91]
	global_load_lds_dwordx4 v136, s[18:19]
	v_mfma_f32_16x16x32_bf16 v[80:83], v[162:165], v[200:203], v[80:83]
	s_add_i32 m0, s29, 0xe000
	v_mfma_f32_16x16x32_bf16 v[72:75], v[170:173], v[200:203], v[72:75]
	s_nop 0
	v_mfma_f32_16x16x32_bf16 v[68:71], v[162:165], v[208:211], v[68:71]
	global_load_lds_dwordx4 v138, s[18:19]
	v_mfma_f32_16x16x32_bf16 v[64:67], v[170:173], v[208:211], v[64:67]
	s_waitcnt lgkmcnt(0)
	s_waitcnt vmcnt(8)
	s_barrier
	v_mfma_f32_16x16x32_bf16 v[124:127], v[150:153], v[188:191], v[124:127]
	ds_read_b128 v[184:187], v144 offset:16384
	s_add_i32 s45, s45, s28
	v_mfma_f32_16x16x32_bf16 v[120:123], v[158:161], v[188:191], v[120:123]
	ds_read_b128 v[192:195], v144 offset:18432
	v_lshl_add_u64 v[140:141], s[20:21], 0, v[178:179]
	v_mfma_f32_16x16x32_bf16 v[116:119], v[150:153], v[196:199], v[116:119]
	ds_read_b128 v[200:203], v144 offset:20480
	s_mov_b32 m0, s45
	v_mfma_f32_16x16x32_bf16 v[108:111], v[158:161], v[196:199], v[108:111]
	ds_read_b128 v[208:211], v144 offset:22528
	s_nop 0
	v_mfma_f32_16x16x32_bf16 v[100:103], v[150:153], v[204:207], v[100:103]
	global_load_lds_dwordx4 v[140:141], off
	v_mfma_f32_16x16x32_bf16 v[92:95], v[158:161], v[204:207], v[92:95]
	s_add_i32 m0, s45, 0x2000
	v_mfma_f32_16x16x32_bf16 v[84:87], v[150:153], v[226:229], v[84:87]
	s_add_u32 s46, s20, 0x80000
	v_mfma_f32_16x16x32_bf16 v[76:79], v[158:161], v[226:229], v[76:79]
	v_lshl_add_u64 v[174:175], s[20:21], 0, v[130:131]
	v_mfma_f32_16x16x32_bf16 v[112:115], v[166:169], v[188:191], v[112:115]
	s_addc_u32 s47, s21, 0
	v_mfma_f32_16x16x32_bf16 v[104:107], v[180:183], v[188:191], v[104:107]
	s_add_i32 s45, s49, s28
	v_mfma_f32_16x16x32_bf16 v[96:99], v[166:169], v[196:199], v[96:99]
	global_load_lds_dwordx4 v[174:175], off
	v_mfma_f32_16x16x32_bf16 v[88:91], v[180:183], v[196:199], v[88:91]
	s_mov_b32 m0, s45
	v_mfma_f32_16x16x32_bf16 v[80:83], v[166:169], v[204:207], v[80:83]
	v_lshl_add_u64 v[230:231], s[22:23], 0, v[132:133]
	v_mfma_f32_16x16x32_bf16 v[72:75], v[180:183], v[204:207], v[72:75]
	global_load_lds_dwordx4 v178, s[46:47]
	v_mfma_f32_16x16x32_bf16 v[68:71], v[166:169], v[226:229], v[68:71]
	s_add_i32 m0, s45, 0x2000
	v_mfma_f32_16x16x32_bf16 v[64:67], v[180:183], v[226:229], v[64:67]
	s_nop 0
	s_waitcnt lgkmcnt(3)
	v_mfma_f32_16x16x32_bf16 v[60:63], v[146:149], v[184:187], v[60:63]
	ds_read_b128 v[188:191], v144 offset:17408
	global_load_lds_dwordx4 v130, s[46:47]
	v_mfma_f32_16x16x32_bf16 v[56:59], v[154:157], v[184:187], v[56:59]
	ds_read_b128 v[196:199], v144 offset:19456
	s_waitcnt lgkmcnt(4)
	v_mfma_f32_16x16x32_bf16 v[52:55], v[146:149], v[192:195], v[52:55]
	ds_read_b128 v[204:207], v144 offset:21504
	v_mfma_f32_16x16x32_bf16 v[44:47], v[154:157], v[192:195], v[44:47]
	ds_read_b128 v[226:229], v144 offset:23552
	s_waitcnt lgkmcnt(5)
	v_mfma_f32_16x16x32_bf16 v[36:39], v[146:149], v[200:203], v[36:39]
	v_mfma_f32_16x16x32_bf16 v[28:31], v[154:157], v[200:203], v[28:31]
	s_waitcnt lgkmcnt(4)
	v_mfma_f32_16x16x32_bf16 v[20:23], v[146:149], v[208:211], v[20:23]
	v_mfma_f32_16x16x32_bf16 v[12:15], v[154:157], v[208:211], v[12:15]
	v_mfma_f32_16x16x32_bf16 v[48:51], v[162:165], v[184:187], v[48:51]
	v_mfma_f32_16x16x32_bf16 v[40:43], v[170:173], v[184:187], v[40:43]
	v_mfma_f32_16x16x32_bf16 v[32:35], v[162:165], v[192:195], v[32:35]
	v_mfma_f32_16x16x32_bf16 v[24:27], v[170:173], v[192:195], v[24:27]
	v_mfma_f32_16x16x32_bf16 v[16:19], v[162:165], v[200:203], v[16:19]
	v_mfma_f32_16x16x32_bf16 v[8:11], v[170:173], v[200:203], v[8:11]
	v_mfma_f32_16x16x32_bf16 v[4:7], v[162:165], v[208:211], v[4:7]
	v_mfma_f32_16x16x32_bf16 v[0:3], v[170:173], v[208:211], v[0:3]
	s_waitcnt lgkmcnt(0)
	s_waitcnt vmcnt(6)
	s_barrier
	v_mfma_f32_16x16x32_bf16 v[60:63], v[150:153], v[188:191], v[60:63]
	ds_read_b128 v[184:187], v144 offset:32768
	v_lshl_add_u64 v[212:213], s[22:23], 0, v[134:135]
	v_mfma_f32_16x16x32_bf16 v[56:59], v[158:161], v[188:191], v[56:59]
	v_add_u32_e32 v154, s63, v142
	ds_read_b128 v[146:149], v154 offset:256
	s_mov_b32 m0, s29
	v_mfma_f32_16x16x32_bf16 v[52:55], v[150:153], v[196:199], v[52:55]
	ds_read_b128 v[154:157], v154 offset:2304
	s_nop 0
	v_mfma_f32_16x16x32_bf16 v[44:47], v[158:161], v[196:199], v[44:47]
	ds_read_b128 v[192:195], v144 offset:34816
	global_load_lds_dwordx4 v[212:213], off
	v_mfma_f32_16x16x32_bf16 v[36:39], v[150:153], v[204:207], v[36:39]
	ds_read_b128 v[200:203], v144 offset:36864
	s_mov_b32 m0, s30
	v_mfma_f32_16x16x32_bf16 v[28:31], v[158:161], v[204:207], v[28:31]
	ds_read_b128 v[208:211], v144 offset:38912
	s_nop 0
	v_mfma_f32_16x16x32_bf16 v[20:23], v[150:153], v[226:229], v[20:23]
	v_add_u32_e32 v170, s75, v142
	ds_read_b128 v[162:165], v170 offset:256
	global_load_lds_dwordx4 v[230:231], off
	v_mfma_f32_16x16x32_bf16 v[12:15], v[158:161], v[226:229], v[12:15]
	ds_read_b128 v[170:173], v170 offset:2304
	s_add_i32 s45, s63, 0x100
	v_mfma_f32_16x16x32_bf16 v[48:51], v[166:169], v[188:191], v[48:51]
	s_add_i32 s46, s75, 0x100
	v_mfma_f32_16x16x32_bf16 v[40:43], v[180:183], v[188:191], v[40:43]
	s_add_u32 s22, s22, 0x80000
	v_mfma_f32_16x16x32_bf16 v[32:35], v[166:169], v[196:199], v[32:35]
	s_addc_u32 s23, s23, 0
	v_mfma_f32_16x16x32_bf16 v[24:27], v[180:183], v[196:199], v[24:27]
	s_mov_b32 m0, s31
	v_mfma_f32_16x16x32_bf16 v[16:19], v[166:169], v[204:207], v[16:19]
	s_nop 0
	v_mfma_f32_16x16x32_bf16 v[8:11], v[180:183], v[204:207], v[8:11]
	global_load_lds_dwordx4 v134, s[22:23]
	v_mfma_f32_16x16x32_bf16 v[4:7], v[166:169], v[226:229], v[4:7]
	s_mov_b32 m0, s34
	v_mfma_f32_16x16x32_bf16 v[0:3], v[180:183], v[226:229], v[0:3]
	s_nop 0
	s_waitcnt lgkmcnt(6)
	v_mfma_f32_16x16x32_bf16 v[124:127], v[146:149], v[184:187], v[124:127]
	ds_read_b128 v[188:191], v144 offset:33792
	global_load_lds_dwordx4 v132, s[22:23]
	s_waitcnt lgkmcnt(6)
	v_mfma_f32_16x16x32_bf16 v[120:123], v[154:157], v[184:187], v[120:123]
	v_add_u32_e32 v158, s63, v142
	ds_read_b128 v[150:153], v158 offset:1280
	s_waitcnt lgkmcnt(6)
	v_mfma_f32_16x16x32_bf16 v[116:119], v[146:149], v[192:195], v[116:119]
	ds_read_b128 v[158:161], v158 offset:3328
	v_mfma_f32_16x16x32_bf16 v[108:111], v[154:157], v[192:195], v[108:111]
	ds_read_b128 v[196:199], v144 offset:35840
	s_waitcnt lgkmcnt(7)
	v_mfma_f32_16x16x32_bf16 v[100:103], v[146:149], v[200:203], v[100:103]
	ds_read_b128 v[204:207], v144 offset:37888
	v_mfma_f32_16x16x32_bf16 v[92:95], v[154:157], v[200:203], v[92:95]
	ds_read_b128 v[226:229], v144 offset:39936
	s_waitcnt lgkmcnt(8)
	v_mfma_f32_16x16x32_bf16 v[84:87], v[146:149], v[208:211], v[84:87]
	v_add_u32_e32 v180, s75, v142
	ds_read_b128 v[166:169], v180 offset:1280
	v_mfma_f32_16x16x32_bf16 v[76:79], v[154:157], v[208:211], v[76:79]
	ds_read_b128 v[180:183], v180 offset:3328
	s_waitcnt lgkmcnt(9)
	v_mfma_f32_16x16x32_bf16 v[112:115], v[162:165], v[184:187], v[112:115]
	s_waitcnt lgkmcnt(8)
	v_mfma_f32_16x16x32_bf16 v[104:107], v[170:173], v[184:187], v[104:107]
	v_mfma_f32_16x16x32_bf16 v[96:99], v[162:165], v[192:195], v[96:99]
	v_mfma_f32_16x16x32_bf16 v[88:91], v[170:173], v[192:195], v[88:91]
	v_mfma_f32_16x16x32_bf16 v[80:83], v[162:165], v[200:203], v[80:83]
	v_mfma_f32_16x16x32_bf16 v[72:75], v[170:173], v[200:203], v[72:75]
	v_mfma_f32_16x16x32_bf16 v[68:71], v[162:165], v[208:211], v[68:71]
	v_mfma_f32_16x16x32_bf16 v[64:67], v[170:173], v[208:211], v[64:67]
	s_waitcnt lgkmcnt(0)
	s_waitcnt vmcnt(8)
	s_barrier
	v_mfma_f32_16x16x32_bf16 v[124:127], v[150:153], v[188:191], v[124:127]
	ds_read_b128 v[184:187], v144 offset:49152
	s_add_i32 s22, s45, s28
	v_mfma_f32_16x16x32_bf16 v[120:123], v[158:161], v[188:191], v[120:123]
	ds_read_b128 v[192:195], v144 offset:51200
	v_lshl_add_u64 v[140:141], v[140:141], 0, s[78:79]
	v_mfma_f32_16x16x32_bf16 v[116:119], v[150:153], v[196:199], v[116:119]
	ds_read_b128 v[200:203], v144 offset:53248
	s_mov_b32 m0, s22
	v_mfma_f32_16x16x32_bf16 v[108:111], v[158:161], v[196:199], v[108:111]
	ds_read_b128 v[208:211], v144 offset:55296
	s_nop 0
	v_mfma_f32_16x16x32_bf16 v[100:103], v[150:153], v[204:207], v[100:103]
	global_load_lds_dwordx4 v[140:141], off
	v_mfma_f32_16x16x32_bf16 v[92:95], v[158:161], v[204:207], v[92:95]
	s_add_i32 m0, s22, 0x2000
	v_mfma_f32_16x16x32_bf16 v[84:87], v[150:153], v[226:229], v[84:87]
	s_add_u32 s20, s20, 0x80080
	v_mfma_f32_16x16x32_bf16 v[76:79], v[158:161], v[226:229], v[76:79]
	v_lshl_add_u64 v[140:141], v[174:175], 0, s[78:79]
	v_mfma_f32_16x16x32_bf16 v[112:115], v[166:169], v[188:191], v[112:115]
	s_addc_u32 s21, s21, 0
	v_mfma_f32_16x16x32_bf16 v[104:107], v[180:183], v[188:191], v[104:107]
	s_add_i32 s22, s46, s28
	v_mfma_f32_16x16x32_bf16 v[96:99], v[166:169], v[196:199], v[96:99]
	global_load_lds_dwordx4 v[140:141], off
	v_mfma_f32_16x16x32_bf16 v[88:91], v[180:183], v[196:199], v[88:91]
	s_mov_b32 m0, s22
	v_mfma_f32_16x16x32_bf16 v[80:83], v[166:169], v[204:207], v[80:83]
	s_nop 0
	v_mfma_f32_16x16x32_bf16 v[72:75], v[180:183], v[204:207], v[72:75]
	global_load_lds_dwordx4 v178, s[20:21]
	v_mfma_f32_16x16x32_bf16 v[68:71], v[166:169], v[226:229], v[68:71]
	s_add_i32 m0, s22, 0x2000
	v_mfma_f32_16x16x32_bf16 v[64:67], v[180:183], v[226:229], v[64:67]
	s_nop 0
	s_waitcnt lgkmcnt(3)
	v_mfma_f32_16x16x32_bf16 v[60:63], v[146:149], v[184:187], v[60:63]
	ds_read_b128 v[188:191], v144 offset:50176
	global_load_lds_dwordx4 v130, s[20:21]
	v_mfma_f32_16x16x32_bf16 v[56:59], v[154:157], v[184:187], v[56:59]
	ds_read_b128 v[196:199], v144 offset:52224
	s_waitcnt lgkmcnt(4)
	v_mfma_f32_16x16x32_bf16 v[52:55], v[146:149], v[192:195], v[52:55]
	ds_read_b128 v[204:207], v144 offset:54272
	v_mfma_f32_16x16x32_bf16 v[44:47], v[154:157], v[192:195], v[44:47]
	ds_read_b128 v[226:229], v144 offset:56320
	s_waitcnt lgkmcnt(5)
	v_mfma_f32_16x16x32_bf16 v[36:39], v[146:149], v[200:203], v[36:39]
	v_mfma_f32_16x16x32_bf16 v[28:31], v[154:157], v[200:203], v[28:31]
	s_waitcnt lgkmcnt(4)
	v_mfma_f32_16x16x32_bf16 v[20:23], v[146:149], v[208:211], v[20:23]
	v_mfma_f32_16x16x32_bf16 v[12:15], v[154:157], v[208:211], v[12:15]
	v_mfma_f32_16x16x32_bf16 v[48:51], v[162:165], v[184:187], v[48:51]
	v_mfma_f32_16x16x32_bf16 v[40:43], v[170:173], v[184:187], v[40:43]
	v_mfma_f32_16x16x32_bf16 v[32:35], v[162:165], v[192:195], v[32:35]
	v_mfma_f32_16x16x32_bf16 v[24:27], v[170:173], v[192:195], v[24:27]
	v_mfma_f32_16x16x32_bf16 v[16:19], v[162:165], v[200:203], v[16:19]
	v_mfma_f32_16x16x32_bf16 v[8:11], v[170:173], v[200:203], v[8:11]
	v_mfma_f32_16x16x32_bf16 v[4:7], v[162:165], v[208:211], v[4:7]
	v_mfma_f32_16x16x32_bf16 v[0:3], v[170:173], v[208:211], v[0:3]
	s_waitcnt lgkmcnt(0)
	s_waitcnt vmcnt(6)
	s_barrier
	v_mfma_f32_16x16x32_bf16 v[60:63], v[150:153], v[188:191], v[60:63]
	ds_read_b128 v[184:187], v144
	v_lshl_add_u64 v[140:141], v[212:213], 0, s[78:79]
	v_mfma_f32_16x16x32_bf16 v[56:59], v[158:161], v[188:191], v[56:59]
	v_add_u32_e32 v154, s93, v142
	ds_read_b128 v[146:149], v154 offset:256
	s_mov_b32 m0, s35
	v_mfma_f32_16x16x32_bf16 v[52:55], v[150:153], v[196:199], v[52:55]
	ds_read_b128 v[154:157], v154 offset:2304
	s_nop 0
	v_mfma_f32_16x16x32_bf16 v[44:47], v[158:161], v[196:199], v[44:47]
	ds_read_b128 v[192:195], v144 offset:2048
	global_load_lds_dwordx4 v[140:141], off
	v_mfma_f32_16x16x32_bf16 v[36:39], v[150:153], v[204:207], v[36:39]
	ds_read_b128 v[200:203], v144 offset:4096
	v_lshl_add_u64 v[140:141], v[230:231], 0, s[78:79]
	v_mfma_f32_16x16x32_bf16 v[28:31], v[158:161], v[204:207], v[28:31]
	ds_read_b128 v[208:211], v144 offset:6144
	s_mov_b32 m0, s36
	v_mfma_f32_16x16x32_bf16 v[20:23], v[150:153], v[226:229], v[20:23]
	v_add_u32_e32 v170, s62, v142
	ds_read_b128 v[162:165], v170 offset:256
	s_nop 0
	v_mfma_f32_16x16x32_bf16 v[12:15], v[158:161], v[226:229], v[12:15]
	ds_read_b128 v[170:173], v170 offset:2304
	global_load_lds_dwordx4 v[140:141], off
	v_mfma_f32_16x16x32_bf16 v[48:51], v[166:169], v[188:191], v[48:51]
	v_mfma_f32_16x16x32_bf16 v[40:43], v[180:183], v[188:191], v[40:43]
	v_mfma_f32_16x16x32_bf16 v[32:35], v[166:169], v[196:199], v[32:35]
	v_mfma_f32_16x16x32_bf16 v[24:27], v[180:183], v[196:199], v[24:27]
	v_mfma_f32_16x16x32_bf16 v[16:19], v[166:169], v[204:207], v[16:19]
	v_mfma_f32_16x16x32_bf16 v[8:11], v[180:183], v[204:207], v[8:11]
	v_mfma_f32_16x16x32_bf16 v[4:7], v[166:169], v[226:229], v[4:7]
	v_mfma_f32_16x16x32_bf16 v[0:3], v[180:183], v[226:229], v[0:3]
	s_add_i32 s44, s44, 2
	s_add_u32 s18, s18, 0x100
	s_addc_u32 s19, s19, 0
	s_add_u32 s42, s42, 0x100
	s_addc_u32 s43, s43, 0
	s_cmp_gt_u32 s44, 29
	s_cbranch_scc0 .Lpg_g7_loop
	s_waitcnt lgkmcnt(0)
	s_and_b64 vcc, exec, s[6:7]
	s_cbranch_vccz .LBB0_837
	s_nop 0
.LBB0_837:
	v_lshl_add_u32 v146, s39, 8, v129
	v_lshl_or_b32 v140, s38, 8, v143
	v_ashrrev_i32_e32 v147, 31, v146
	v_ashrrev_i32_e32 v141, 31, v140
	v_lshlrev_b64 v[148:149], 12, v[146:147]
	v_lshl_add_u64 v[148:149], s[4:5], 0, v[148:149]
	v_lshlrev_b64 v[150:151], 1, v[140:141]
	v_lshl_add_u64 v[140:141], v[148:149], 0, v[150:151]
	v_cvt_pk_bf16_f32 v124, v124, v125
	v_cvt_pk_bf16_f32 v125, v126, v127
	v_cvt_pk_bf16_f32 v126, v120, v121
	v_cvt_pk_bf16_f32 v127, v122, v123
	global_store_dwordx4 v[140:141], v[124:127], off
	v_cvt_pk_bf16_f32 v112, v112, v113
	v_cvt_pk_bf16_f32 v113, v114, v115
	v_cvt_pk_bf16_f32 v114, v104, v105
	v_or_b32_e32 v104, 16, v146
	v_ashrrev_i32_e32 v105, 31, v104
	v_lshlrev_b64 v[104:105], 12, v[104:105]
	v_lshl_add_u64 v[104:105], s[4:5], 0, v[104:105]
	v_cvt_pk_bf16_f32 v115, v106, v107
	global_store_dwordx4 v[140:141], v[112:115], off offset:256
	s_mov_b32 s11, 0x80000
	s_mov_b64 s[18:19], 0x80000
	v_lshl_add_u64 v[112:113], v[104:105], 0, v[150:151]
	v_cvt_pk_bf16_f32 v104, v116, v117
	v_cvt_pk_bf16_f32 v105, v118, v119
	v_cvt_pk_bf16_f32 v106, v108, v109
	v_cvt_pk_bf16_f32 v107, v110, v111
	global_store_dwordx4 v[112:113], v[104:107], off
	v_cvt_pk_bf16_f32 v96, v96, v97
	v_cvt_pk_bf16_f32 v97, v98, v99
	v_cvt_pk_bf16_f32 v98, v88, v89
	v_or_b32_e32 v88, 32, v146
	v_ashrrev_i32_e32 v89, 31, v88
	v_lshlrev_b64 v[88:89], 12, v[88:89]
	v_lshl_add_u64 v[88:89], s[4:5], 0, v[88:89]
	v_cvt_pk_bf16_f32 v99, v90, v91
	global_store_dwordx4 v[112:113], v[96:99], off offset:256
	s_nop 1
	v_lshl_add_u64 v[96:97], v[88:89], 0, v[150:151]
	v_cvt_pk_bf16_f32 v88, v100, v101
	v_cvt_pk_bf16_f32 v89, v102, v103
	v_cvt_pk_bf16_f32 v90, v92, v93
	v_cvt_pk_bf16_f32 v91, v94, v95
	global_store_dwordx4 v[96:97], v[88:91], off
	v_cvt_pk_bf16_f32 v80, v80, v81
	v_cvt_pk_bf16_f32 v81, v82, v83
	v_cvt_pk_bf16_f32 v82, v72, v73
	v_or_b32_e32 v72, 48, v146
	v_ashrrev_i32_e32 v73, 31, v72
	v_lshlrev_b64 v[72:73], 12, v[72:73]
	v_lshl_add_u64 v[72:73], s[4:5], 0, v[72:73]
	v_cvt_pk_bf16_f32 v83, v74, v75
	global_store_dwordx4 v[96:97], v[80:83], off offset:256
	s_nop 1
	v_lshl_add_u64 v[80:81], v[72:73], 0, v[150:151]
	v_cvt_pk_bf16_f32 v72, v84, v85
	v_cvt_pk_bf16_f32 v73, v86, v87
	v_cvt_pk_bf16_f32 v74, v76, v77
	v_cvt_pk_bf16_f32 v75, v78, v79
	global_store_dwordx4 v[80:81], v[72:75], off
	v_cvt_pk_bf16_f32 v68, v68, v69
	v_cvt_pk_bf16_f32 v69, v70, v71
	v_cvt_pk_bf16_f32 v70, v64, v65
	v_cvt_pk_bf16_f32 v71, v66, v67
	global_store_dwordx4 v[80:81], v[68:71], off offset:256
	v_cvt_pk_bf16_f32 v60, v60, v61
	v_cvt_pk_bf16_f32 v61, v62, v63
	v_cvt_pk_bf16_f32 v62, v56, v57
	v_add_co_u32_e32 v56, vcc, s11, v140
	v_lshl_add_u64 v[64:65], v[140:141], 0, s[18:19]
	s_nop 0
	v_addc_co_u32_e32 v57, vcc, 0, v141, vcc
	s_mov_b32 s11, 0x90000
	v_cvt_pk_bf16_f32 v63, v58, v59
	global_store_dwordx4 v[56:57], v[60:63], off
	v_cvt_pk_bf16_f32 v48, v48, v49
	v_cvt_pk_bf16_f32 v49, v50, v51
	v_cvt_pk_bf16_f32 v50, v40, v41
	v_cvt_pk_bf16_f32 v51, v42, v43
	global_store_dwordx4 v[64:65], v[48:51], off offset:256
	s_mov_b64 s[18:19], 0x90000
	v_cvt_pk_bf16_f32 v40, v52, v53
	v_cvt_pk_bf16_f32 v41, v54, v55
	v_cvt_pk_bf16_f32 v42, v44, v45
	v_add_co_u32_e32 v44, vcc, s11, v140
	v_lshl_add_u64 v[48:49], v[140:141], 0, s[18:19]
	s_nop 0
	v_addc_co_u32_e32 v45, vcc, 0, v141, vcc
	s_mov_b32 s11, 0xa0000
	v_cvt_pk_bf16_f32 v43, v46, v47
	global_store_dwordx4 v[44:45], v[40:43], off
	v_cvt_pk_bf16_f32 v32, v32, v33
	v_cvt_pk_bf16_f32 v33, v34, v35
	v_cvt_pk_bf16_f32 v34, v24, v25
	v_cvt_pk_bf16_f32 v35, v26, v27
	global_store_dwordx4 v[48:49], v[32:35], off offset:256
	s_mov_b64 s[18:19], 0xa0000
	v_cvt_pk_bf16_f32 v24, v36, v37
	v_cvt_pk_bf16_f32 v25, v38, v39
	v_cvt_pk_bf16_f32 v26, v28, v29
	v_add_co_u32_e32 v28, vcc, s11, v140
	v_lshl_add_u64 v[32:33], v[140:141], 0, s[18:19]
	s_nop 0
	v_addc_co_u32_e32 v29, vcc, 0, v141, vcc
	s_mov_b32 s11, 0xb0000
	v_cvt_pk_bf16_f32 v27, v30, v31
	global_store_dwordx4 v[28:29], v[24:27], off
	v_cvt_pk_bf16_f32 v16, v16, v17
	v_cvt_pk_bf16_f32 v17, v18, v19
	v_cvt_pk_bf16_f32 v18, v8, v9
	v_cvt_pk_bf16_f32 v19, v10, v11
	global_store_dwordx4 v[32:33], v[16:19], off offset:256
	v_cvt_pk_bf16_f32 v8, v20, v21
	v_cvt_pk_bf16_f32 v9, v22, v23
	v_cvt_pk_bf16_f32 v10, v12, v13
	v_add_co_u32_e32 v12, vcc, s11, v140
	s_mov_b64 s[18:19], 0xb0000
	s_nop 0
	v_addc_co_u32_e32 v13, vcc, 0, v141, vcc
	v_lshl_add_u64 v[16:17], v[140:141], 0, s[18:19]
	s_andn2_b64 vcc, exec, s[0:1]
	s_mov_b64 s[0:1], -1
	v_cvt_pk_bf16_f32 v11, v14, v15
	global_store_dwordx4 v[12:13], v[8:11], off
	v_cvt_pk_bf16_f32 v4, v4, v5
	v_cvt_pk_bf16_f32 v5, v6, v7
	v_cvt_pk_bf16_f32 v6, v0, v1
	v_cvt_pk_bf16_f32 v7, v2, v3
	global_store_dwordx4 v[16:17], v[4:7], off offset:256
	s_cbranch_vccnz .LBB0_826
	s_andn2_b64 vcc, exec, s[2:3]
	s_cbranch_vccnz .LBB0_825
	s_nop 0
	s_branch .LBB0_825

.LBB0_1013:
	v_readlane_b32 s10, v253, 23
	s_mov_b64 s[4:5], s[94:95]
	s_mov_b64 s[2:3], s[94:95]
	s_mov_b64 s[0:1], s[94:95]
	s_waitcnt vmcnt(0)
	v_mov_b32_e32 v14, v176
	v_readlane_b32 s11, v253, 24
	s_andn2_b64 vcc, exec, s[10:11]
	v_readfirstlane_b32 s10, v14
	s_cbranch_vccnz .LBB0_1033
	v_lshlrev_b32_e32 v0, 4, v14
	v_add_u32_e32 v1, 0x2000, v0
	v_ashrrev_i32_e32 v2, 31, v1
	v_lshrrev_b32_e32 v2, 22, v2
	v_add_u32_e32 v2, v1, v2
	v_ashrrev_i32_e32 v8, 10, v2
	v_mul_i32_i24_e32 v2, 0x400, v8
	s_load_dwordx2 s[4:5], s[4:5], 0xc0
	s_nop 0
	s_load_dwordx2 s[2:3], s[2:3], 0xc0
	v_sub_u32_e32 v1, v1, v2
	v_lshrrev_b32_e32 v2, 4, v1
	v_bitop3_b32 v1, v2, v1, 32 bitop3:0x6c
	v_ashrrev_i32_e32 v2, 31, v1
	s_waitcnt lgkmcnt(0)
	s_add_u32 s26, s4, 0x17800000
	v_lshrrev_b32_e32 v2, 26, v2
	s_mul_i32 s11, s82, 0x5d00000
	s_addc_u32 s27, s5, 0
	v_add_u32_e32 v2, v1, v2
	v_lshlrev_b32_e32 v3, 3, v8
	s_add_u32 s2, s2, s11
	v_ashrrev_i32_e32 v9, 6, v2
	v_and_b32_e32 v3, -16, v3
	s_addc_u32 s3, s3, 0
	v_add_u32_e32 v3, v9, v3
	s_add_u32 s28, s2, 0x2100000
	v_and_b32_e32 v4, 3, v9
	s_mov_b32 s2, 0xfffe0
	v_lshrrev_b32_e32 v5, 2, v3
	v_lshlrev_b32_e32 v6, 1, v3
	v_and_b32_e32 v2, 0xc0, v2
	v_and_or_b32 v4, v3, s2, v4
	v_and_b32_e32 v5, 4, v5
	v_and_b32_e32 v6, 24, v6
	v_sub_u32_e32 v1, v1, v2
	v_or3_b32 v4, v4, v5, v6
	v_lshlrev_b32_e32 v5, 5, v8
	v_ashrrev_i16_sdwa v1, v177, sext(v1) dst_sel:DWORD dst_unused:UNUSED_PAD src0_sel:DWORD src1_sel:BYTE_0
	v_and_b32_e32 v5, 32, v5
	v_bfe_i32 v10, v1, 0, 16
	v_add_lshl_u32 v1, v5, v10, 1
	v_lshl_add_u32 v130, v4, 12, v1
	v_lshl_add_u32 v132, v3, 12, v1
	v_bfe_i32 v1, v14, 27, 1
	v_lshrrev_b32_e32 v1, 22, v1
	v_add_u32_e32 v1, v0, v1
	v_and_b32_e32 v1, 0xfffffc00, v1
	v_sub_u32_e32 v0, v0, v1
	v_lshrrev_b32_e32 v1, 4, v0
	v_ashrrev_i32_e32 v2, 31, v14
	v_bitop3_b32 v0, v1, v0, 32 bitop3:0x6c
	v_lshrrev_b32_e32 v2, 26, v2
	v_ashrrev_i32_e32 v1, 31, v0
	v_add_u32_e32 v2, v14, v2
	v_lshrrev_b32_e32 v1, 26, v1
	v_ashrrev_i32_e32 v12, 6, v2
	v_add_u32_e32 v1, v0, v1
	v_lshlrev_b32_e32 v2, 3, v12
	v_ashrrev_i32_e32 v11, 6, v1
	v_and_b32_e32 v2, -16, v2
	v_add_u32_e32 v2, v11, v2
	v_and_b32_e32 v3, 3, v11
	v_lshrrev_b32_e32 v4, 2, v2
	v_lshlrev_b32_e32 v5, 1, v2
	v_and_b32_e32 v1, 0xc0, v1
	s_addc_u32 s29, s3, 0
	s_ashr_i32 s11, s10, 6
	v_and_or_b32 v3, v2, s2, v3
	v_and_b32_e32 v4, 4, v4
	v_and_b32_e32 v5, 24, v5
	v_sub_u32_e32 v0, v0, v1
	s_ashr_i32 s12, s10, 8
	s_lshl_b32 s30, s11, 10
	v_or3_b32 v3, v3, v4, v5
	v_lshlrev_b32_e32 v4, 5, v12
	v_ashrrev_i16_sdwa v0, v177, sext(v0) dst_sel:DWORD dst_unused:UNUSED_PAD src0_sel:DWORD src1_sel:BYTE_0
	v_readlane_b32 s2, v253, 34
	v_and_b32_e32 v4, 32, v4
	v_bfe_i32 v13, v0, 0, 16
	v_readlane_b32 s3, v253, 35
	s_add_u32 s22, s28, s2
	v_add_lshl_u32 v0, v4, v13, 1
	s_addc_u32 s23, s29, s3
	s_add_i32 s31, s30, 0x100
	v_lshl_add_u32 v178, v3, 12, v0
	s_add_i32 m0, s31, 0x10000
	v_lshl_add_u32 v134, v2, 12, v0
	global_load_lds_dwordx4 v178, s[22:23]
	s_add_i32 m0, s31, 0x12000
	s_add_u32 s2, s22, 0x80000
	global_load_lds_dwordx4 v130, s[22:23]
	s_addc_u32 s3, s23, 0
	s_add_i32 m0, s31, 0x14000
	s_load_dwordx2 s[0:1], s[0:1], 0xc0
	global_load_lds_dwordx4 v178, s[2:3]
	s_add_i32 m0, s31, 0x16000
	v_mov_b32_e32 v131, v179
	global_load_lds_dwordx4 v130, s[2:3]
	v_readlane_b32 s2, v254, 3
	v_readlane_b32 s3, v254, 4
	s_add_u32 s20, s26, s2
	s_addc_u32 s21, s27, s3
	s_add_i32 s34, s31, 0x2000
	s_mov_b32 m0, s31
	s_add_u32 s2, s20, 0x80000
	global_load_lds_dwordx4 v134, s[20:21]
	s_mov_b32 m0, s34
	s_addc_u32 s3, s21, 0
	s_add_i32 s35, s31, 0x4000
	global_load_lds_dwordx4 v132, s[20:21]
	s_mov_b32 m0, s35
	s_add_i32 s36, s31, 0x6000
	global_load_lds_dwordx4 v134, s[2:3]
	s_mov_b32 m0, s36
	v_mov_b32_e32 v135, v179
	global_load_lds_dwordx4 v132, s[2:3]
	v_mov_b32_e32 v133, v179
	s_cmp_eq_u32 s12, 1
	v_lshl_add_u64 v[6:7], s[22:23], 0, v[178:179]
	v_lshl_add_u64 v[4:5], s[22:23], 0, v[130:131]
	v_lshl_add_u64 v[0:1], s[20:21], 0, v[134:135]
	s_cselect_b64 s[2:3], -1, 0
	s_cmp_lg_u32 s12, 1
	v_lshl_add_u64 v[2:3], s[20:21], 0, v[132:133]
	s_cbranch_scc1 .LBB0_1016
	s_nop 0

.Lpg_g9_loop:
	s_waitcnt lgkmcnt(6)
	v_mfma_f32_16x16x32_bf16 v[124:127], v[146:149], v[184:187], v[124:127]
	ds_read_b128 v[188:191], v144 offset:1024
	s_add_u32 s22, s20, 0xfff80080
	s_waitcnt lgkmcnt(6)
	v_mfma_f32_16x16x32_bf16 v[120:123], v[154:157], v[184:187], v[120:123]
	v_add_u32_e32 v158, s93, v142
	ds_read_b128 v[150:153], v158 offset:1280
	s_addc_u32 s23, s21, -1
	s_waitcnt lgkmcnt(6)
	v_mfma_f32_16x16x32_bf16 v[108:111], v[146:149], v[192:195], v[108:111]
	ds_read_b128 v[158:161], v158 offset:3328
	s_add_i32 s47, s93, 0x100
	v_mfma_f32_16x16x32_bf16 v[104:107], v[154:157], v[192:195], v[104:107]
	ds_read_b128 v[196:199], v144 offset:3072
	s_cmp_eq_u32 s46, 28
	s_waitcnt lgkmcnt(7)
	v_mfma_f32_16x16x32_bf16 v[92:95], v[146:149], v[200:203], v[92:95]
	ds_read_b128 v[204:207], v144 offset:5120
	s_cselect_b32 s25, s15, s23
	v_mfma_f32_16x16x32_bf16 v[88:91], v[154:157], v[200:203], v[88:91]
	ds_read_b128 v[226:229], v144 offset:7168
	s_cselect_b32 s24, s42, s22
	s_waitcnt lgkmcnt(8)
	v_mfma_f32_16x16x32_bf16 v[76:79], v[146:149], v[208:211], v[76:79]
	v_add_u32_e32 v180, s62, v142
	ds_read_b128 v[166:169], v180 offset:1280
	s_cselect_b32 s23, s13, s45
	v_mfma_f32_16x16x32_bf16 v[72:75], v[154:157], v[208:211], v[72:75]
	ds_read_b128 v[180:183], v180 offset:3328
	s_cselect_b32 s22, s43, s44
	s_waitcnt lgkmcnt(9)
	v_mfma_f32_16x16x32_bf16 v[116:119], v[162:165], v[184:187], v[116:119]
	s_add_i32 s49, s62, 0x100
	s_waitcnt lgkmcnt(8)
	v_mfma_f32_16x16x32_bf16 v[112:115], v[170:173], v[184:187], v[112:115]
	s_add_i32 m0, s31, 0xc000
	v_mfma_f32_16x16x32_bf16 v[100:103], v[162:165], v[192:195], v[100:103]
	s_nop 0
	v_mfma_f32_16x16x32_bf16 v[96:99], v[170:173], v[192:195], v[96:99]
	global_load_lds_dwordx4 v136, s[20:21]
	v_mfma_f32_16x16x32_bf16 v[84:87], v[162:165], v[200:203], v[84:87]
	s_add_i32 m0, s31, 0xe000
	v_mfma_f32_16x16x32_bf16 v[80:83], v[170:173], v[200:203], v[80:83]
	s_nop 0
	v_mfma_f32_16x16x32_bf16 v[68:71], v[162:165], v[208:211], v[68:71]
	global_load_lds_dwordx4 v138, s[20:21]
	v_mfma_f32_16x16x32_bf16 v[64:67], v[170:173], v[208:211], v[64:67]
	s_waitcnt lgkmcnt(0)
	s_waitcnt vmcnt(8)
	s_barrier
	v_mfma_f32_16x16x32_bf16 v[124:127], v[150:153], v[188:191], v[124:127]
	ds_read_b128 v[184:187], v144 offset:16384
	s_add_i32 s47, s47, s30
	v_mfma_f32_16x16x32_bf16 v[120:123], v[158:161], v[188:191], v[120:123]
	ds_read_b128 v[192:195], v144 offset:18432
	v_lshl_add_u64 v[140:141], s[22:23], 0, v[178:179]
	v_mfma_f32_16x16x32_bf16 v[108:111], v[150:153], v[196:199], v[108:111]
	ds_read_b128 v[200:203], v144 offset:20480
	s_mov_b32 m0, s47
	v_mfma_f32_16x16x32_bf16 v[104:107], v[158:161], v[196:199], v[104:107]
	ds_read_b128 v[208:211], v144 offset:22528
	s_nop 0
	v_mfma_f32_16x16x32_bf16 v[92:95], v[150:153], v[204:207], v[92:95]
	global_load_lds_dwordx4 v[140:141], off
	v_mfma_f32_16x16x32_bf16 v[88:91], v[158:161], v[204:207], v[88:91]
	s_add_i32 m0, s47, 0x2000
	v_mfma_f32_16x16x32_bf16 v[76:79], v[150:153], v[226:229], v[76:79]
	s_add_u32 s50, s22, 0x80000
	v_mfma_f32_16x16x32_bf16 v[72:75], v[158:161], v[226:229], v[72:75]
	v_lshl_add_u64 v[174:175], s[22:23], 0, v[130:131]
	v_mfma_f32_16x16x32_bf16 v[116:119], v[166:169], v[188:191], v[116:119]
	s_addc_u32 s51, s23, 0
	v_mfma_f32_16x16x32_bf16 v[112:115], v[180:183], v[188:191], v[112:115]
	s_add_i32 s47, s49, s30
	v_mfma_f32_16x16x32_bf16 v[100:103], v[166:169], v[196:199], v[100:103]
	global_load_lds_dwordx4 v[174:175], off
	v_mfma_f32_16x16x32_bf16 v[96:99], v[180:183], v[196:199], v[96:99]
	s_mov_b32 m0, s47
	v_mfma_f32_16x16x32_bf16 v[84:87], v[166:169], v[204:207], v[84:87]
	v_lshl_add_u64 v[230:231], s[24:25], 0, v[132:133]
	v_mfma_f32_16x16x32_bf16 v[80:83], v[180:183], v[204:207], v[80:83]
	global_load_lds_dwordx4 v178, s[50:51]
	v_mfma_f32_16x16x32_bf16 v[68:71], v[166:169], v[226:229], v[68:71]
	s_add_i32 m0, s47, 0x2000
	v_mfma_f32_16x16x32_bf16 v[64:67], v[180:183], v[226:229], v[64:67]
	s_nop 0
	s_waitcnt lgkmcnt(3)
	v_mfma_f32_16x16x32_bf16 v[60:63], v[146:149], v[184:187], v[60:63]
	ds_read_b128 v[188:191], v144 offset:17408
	global_load_lds_dwordx4 v130, s[50:51]
	v_mfma_f32_16x16x32_bf16 v[56:59], v[154:157], v[184:187], v[56:59]
	ds_read_b128 v[196:199], v144 offset:19456
	s_waitcnt lgkmcnt(4)
	v_mfma_f32_16x16x32_bf16 v[44:47], v[146:149], v[192:195], v[44:47]
	ds_read_b128 v[204:207], v144 offset:21504
	v_mfma_f32_16x16x32_bf16 v[40:43], v[154:157], v[192:195], v[40:43]
	ds_read_b128 v[226:229], v144 offset:23552
	s_waitcnt lgkmcnt(5)
	v_mfma_f32_16x16x32_bf16 v[28:31], v[146:149], v[200:203], v[28:31]
	v_mfma_f32_16x16x32_bf16 v[24:27], v[154:157], v[200:203], v[24:27]
	s_waitcnt lgkmcnt(4)
	v_mfma_f32_16x16x32_bf16 v[12:15], v[146:149], v[208:211], v[12:15]
	v_mfma_f32_16x16x32_bf16 v[8:11], v[154:157], v[208:211], v[8:11]
	v_mfma_f32_16x16x32_bf16 v[52:55], v[162:165], v[184:187], v[52:55]
	v_mfma_f32_16x16x32_bf16 v[48:51], v[170:173], v[184:187], v[48:51]
	v_mfma_f32_16x16x32_bf16 v[36:39], v[162:165], v[192:195], v[36:39]
	v_mfma_f32_16x16x32_bf16 v[32:35], v[170:173], v[192:195], v[32:35]
	v_mfma_f32_16x16x32_bf16 v[20:23], v[162:165], v[200:203], v[20:23]
	v_mfma_f32_16x16x32_bf16 v[16:19], v[170:173], v[200:203], v[16:19]
	v_mfma_f32_16x16x32_bf16 v[4:7], v[162:165], v[208:211], v[4:7]
	v_mfma_f32_16x16x32_bf16 v[0:3], v[170:173], v[208:211], v[0:3]
	s_waitcnt lgkmcnt(0)
	s_waitcnt vmcnt(6)
	s_barrier
	v_mfma_f32_16x16x32_bf16 v[60:63], v[150:153], v[188:191], v[60:63]
	ds_read_b128 v[184:187], v144 offset:32768
	v_lshl_add_u64 v[212:213], s[24:25], 0, v[134:135]
	v_mfma_f32_16x16x32_bf16 v[56:59], v[158:161], v[188:191], v[56:59]
	v_add_u32_e32 v154, s63, v142
	ds_read_b128 v[146:149], v154 offset:256
	s_mov_b32 m0, s31
	v_mfma_f32_16x16x32_bf16 v[44:47], v[150:153], v[196:199], v[44:47]
	ds_read_b128 v[154:157], v154 offset:2304
	s_nop 0
	v_mfma_f32_16x16x32_bf16 v[40:43], v[158:161], v[196:199], v[40:43]
	ds_read_b128 v[192:195], v144 offset:34816
	global_load_lds_dwordx4 v[212:213], off
	v_mfma_f32_16x16x32_bf16 v[28:31], v[150:153], v[204:207], v[28:31]
	ds_read_b128 v[200:203], v144 offset:36864
	s_mov_b32 m0, s34
	v_mfma_f32_16x16x32_bf16 v[24:27], v[158:161], v[204:207], v[24:27]
	ds_read_b128 v[208:211], v144 offset:38912
	s_nop 0
	v_mfma_f32_16x16x32_bf16 v[12:15], v[150:153], v[226:229], v[12:15]
	v_add_u32_e32 v170, s75, v142
	ds_read_b128 v[162:165], v170 offset:256
	global_load_lds_dwordx4 v[230:231], off
	v_mfma_f32_16x16x32_bf16 v[8:11], v[158:161], v[226:229], v[8:11]
	ds_read_b128 v[170:173], v170 offset:2304
	s_add_i32 s47, s63, 0x100
	v_mfma_f32_16x16x32_bf16 v[52:55], v[166:169], v[188:191], v[52:55]
	s_add_i32 s49, s75, 0x100
	v_mfma_f32_16x16x32_bf16 v[48:51], v[180:183], v[188:191], v[48:51]
	s_add_u32 s24, s24, 0x80000
	v_mfma_f32_16x16x32_bf16 v[36:39], v[166:169], v[196:199], v[36:39]
	s_addc_u32 s25, s25, 0
	v_mfma_f32_16x16x32_bf16 v[32:35], v[180:183], v[196:199], v[32:35]
	s_mov_b32 m0, s35
	v_mfma_f32_16x16x32_bf16 v[20:23], v[166:169], v[204:207], v[20:23]
	s_nop 0
	v_mfma_f32_16x16x32_bf16 v[16:19], v[180:183], v[204:207], v[16:19]
	global_load_lds_dwordx4 v134, s[24:25]
	v_mfma_f32_16x16x32_bf16 v[4:7], v[166:169], v[226:229], v[4:7]
	s_mov_b32 m0, s36
	v_mfma_f32_16x16x32_bf16 v[0:3], v[180:183], v[226:229], v[0:3]
	s_nop 0
	s_waitcnt lgkmcnt(6)
	v_mfma_f32_16x16x32_bf16 v[124:127], v[146:149], v[184:187], v[124:127]
	ds_read_b128 v[188:191], v144 offset:33792
	global_load_lds_dwordx4 v132, s[24:25]
	s_waitcnt lgkmcnt(6)
	v_mfma_f32_16x16x32_bf16 v[120:123], v[154:157], v[184:187], v[120:123]
	v_add_u32_e32 v158, s63, v142
	ds_read_b128 v[150:153], v158 offset:1280
	s_waitcnt lgkmcnt(6)
	v_mfma_f32_16x16x32_bf16 v[108:111], v[146:149], v[192:195], v[108:111]
	ds_read_b128 v[158:161], v158 offset:3328
	v_mfma_f32_16x16x32_bf16 v[104:107], v[154:157], v[192:195], v[104:107]
	ds_read_b128 v[196:199], v144 offset:35840
	s_waitcnt lgkmcnt(7)
	v_mfma_f32_16x16x32_bf16 v[92:95], v[146:149], v[200:203], v[92:95]
	ds_read_b128 v[204:207], v144 offset:37888
	v_mfma_f32_16x16x32_bf16 v[88:91], v[154:157], v[200:203], v[88:91]
	ds_read_b128 v[226:229], v144 offset:39936
	s_waitcnt lgkmcnt(8)
	v_mfma_f32_16x16x32_bf16 v[76:79], v[146:149], v[208:211], v[76:79]
	v_add_u32_e32 v180, s75, v142
	ds_read_b128 v[166:169], v180 offset:1280
	v_mfma_f32_16x16x32_bf16 v[72:75], v[154:157], v[208:211], v[72:75]
	ds_read_b128 v[180:183], v180 offset:3328
	s_waitcnt lgkmcnt(9)
	v_mfma_f32_16x16x32_bf16 v[116:119], v[162:165], v[184:187], v[116:119]
	s_waitcnt lgkmcnt(8)
	v_mfma_f32_16x16x32_bf16 v[112:115], v[170:173], v[184:187], v[112:115]
	v_mfma_f32_16x16x32_bf16 v[100:103], v[162:165], v[192:195], v[100:103]
	v_mfma_f32_16x16x32_bf16 v[96:99], v[170:173], v[192:195], v[96:99]
	v_mfma_f32_16x16x32_bf16 v[84:87], v[162:165], v[200:203], v[84:87]
	v_mfma_f32_16x16x32_bf16 v[80:83], v[170:173], v[200:203], v[80:83]
	v_mfma_f32_16x16x32_bf16 v[68:71], v[162:165], v[208:211], v[68:71]
	v_mfma_f32_16x16x32_bf16 v[64:67], v[170:173], v[208:211], v[64:67]
	s_waitcnt lgkmcnt(0)
	s_waitcnt vmcnt(8)
	s_barrier
	v_mfma_f32_16x16x32_bf16 v[124:127], v[150:153], v[188:191], v[124:127]
	ds_read_b128 v[184:187], v144 offset:49152
	s_add_i32 s24, s47, s30
	v_mfma_f32_16x16x32_bf16 v[120:123], v[158:161], v[188:191], v[120:123]
	ds_read_b128 v[192:195], v144 offset:51200
	v_lshl_add_u64 v[140:141], v[140:141], 0, s[78:79]
	v_mfma_f32_16x16x32_bf16 v[108:111], v[150:153], v[196:199], v[108:111]
	ds_read_b128 v[200:203], v144 offset:53248
	s_mov_b32 m0, s24
	v_mfma_f32_16x16x32_bf16 v[104:107], v[158:161], v[196:199], v[104:107]
	ds_read_b128 v[208:211], v144 offset:55296
	s_nop 0
	v_mfma_f32_16x16x32_bf16 v[92:95], v[150:153], v[204:207], v[92:95]
	global_load_lds_dwordx4 v[140:141], off
	v_mfma_f32_16x16x32_bf16 v[88:91], v[158:161], v[204:207], v[88:91]
	s_add_i32 m0, s24, 0x2000
	v_mfma_f32_16x16x32_bf16 v[76:79], v[150:153], v[226:229], v[76:79]
	s_add_u32 s22, s22, 0x80080
	v_mfma_f32_16x16x32_bf16 v[72:75], v[158:161], v[226:229], v[72:75]
	v_lshl_add_u64 v[140:141], v[174:175], 0, s[78:79]
	v_mfma_f32_16x16x32_bf16 v[116:119], v[166:169], v[188:191], v[116:119]
	s_addc_u32 s23, s23, 0
	v_mfma_f32_16x16x32_bf16 v[112:115], v[180:183], v[188:191], v[112:115]
	s_add_i32 s24, s49, s30
	v_mfma_f32_16x16x32_bf16 v[100:103], v[166:169], v[196:199], v[100:103]
	global_load_lds_dwordx4 v[140:141], off
	v_mfma_f32_16x16x32_bf16 v[96:99], v[180:183], v[196:199], v[96:99]
	s_mov_b32 m0, s24
	v_mfma_f32_16x16x32_bf16 v[84:87], v[166:169], v[204:207], v[84:87]
	s_nop 0
	v_mfma_f32_16x16x32_bf16 v[80:83], v[180:183], v[204:207], v[80:83]
	global_load_lds_dwordx4 v178, s[22:23]
	v_mfma_f32_16x16x32_bf16 v[68:71], v[166:169], v[226:229], v[68:71]
	s_add_i32 m0, s24, 0x2000
	v_mfma_f32_16x16x32_bf16 v[64:67], v[180:183], v[226:229], v[64:67]
	s_nop 0
	s_waitcnt lgkmcnt(3)
	v_mfma_f32_16x16x32_bf16 v[60:63], v[146:149], v[184:187], v[60:63]
	ds_read_b128 v[188:191], v144 offset:50176
	global_load_lds_dwordx4 v130, s[22:23]
	v_mfma_f32_16x16x32_bf16 v[56:59], v[154:157], v[184:187], v[56:59]
	ds_read_b128 v[196:199], v144 offset:52224
	s_waitcnt lgkmcnt(4)
	v_mfma_f32_16x16x32_bf16 v[44:47], v[146:149], v[192:195], v[44:47]
	ds_read_b128 v[204:207], v144 offset:54272
	v_mfma_f32_16x16x32_bf16 v[40:43], v[154:157], v[192:195], v[40:43]
	ds_read_b128 v[226:229], v144 offset:56320
	s_waitcnt lgkmcnt(5)
	v_mfma_f32_16x16x32_bf16 v[28:31], v[146:149], v[200:203], v[28:31]
	v_mfma_f32_16x16x32_bf16 v[24:27], v[154:157], v[200:203], v[24:27]
	s_waitcnt lgkmcnt(4)
	v_mfma_f32_16x16x32_bf16 v[12:15], v[146:149], v[208:211], v[12:15]
	v_mfma_f32_16x16x32_bf16 v[8:11], v[154:157], v[208:211], v[8:11]
	v_mfma_f32_16x16x32_bf16 v[52:55], v[162:165], v[184:187], v[52:55]
	v_mfma_f32_16x16x32_bf16 v[48:51], v[170:173], v[184:187], v[48:51]
	v_mfma_f32_16x16x32_bf16 v[36:39], v[162:165], v[192:195], v[36:39]
	v_mfma_f32_16x16x32_bf16 v[32:35], v[170:173], v[192:195], v[32:35]
	v_mfma_f32_16x16x32_bf16 v[20:23], v[162:165], v[200:203], v[20:23]
	v_mfma_f32_16x16x32_bf16 v[16:19], v[170:173], v[200:203], v[16:19]
	v_mfma_f32_16x16x32_bf16 v[4:7], v[162:165], v[208:211], v[4:7]
	v_mfma_f32_16x16x32_bf16 v[0:3], v[170:173], v[208:211], v[0:3]
	s_waitcnt lgkmcnt(0)
	s_waitcnt vmcnt(6)
	s_barrier
	v_mfma_f32_16x16x32_bf16 v[60:63], v[150:153], v[188:191], v[60:63]
	ds_read_b128 v[184:187], v144
	v_lshl_add_u64 v[140:141], v[212:213], 0, s[78:79]
	v_mfma_f32_16x16x32_bf16 v[56:59], v[158:161], v[188:191], v[56:59]
	v_add_u32_e32 v154, s93, v142
	ds_read_b128 v[146:149], v154 offset:256
	s_mov_b32 m0, s37
	v_mfma_f32_16x16x32_bf16 v[44:47], v[150:153], v[196:199], v[44:47]
	ds_read_b128 v[154:157], v154 offset:2304
	s_nop 0
	v_mfma_f32_16x16x32_bf16 v[40:43], v[158:161], v[196:199], v[40:43]
	ds_read_b128 v[192:195], v144 offset:2048
	global_load_lds_dwordx4 v[140:141], off
	v_mfma_f32_16x16x32_bf16 v[28:31], v[150:153], v[204:207], v[28:31]
	ds_read_b128 v[200:203], v144 offset:4096
	v_lshl_add_u64 v[140:141], v[230:231], 0, s[78:79]
	v_mfma_f32_16x16x32_bf16 v[24:27], v[158:161], v[204:207], v[24:27]
	ds_read_b128 v[208:211], v144 offset:6144
	s_mov_b32 m0, s38
	v_mfma_f32_16x16x32_bf16 v[12:15], v[150:153], v[226:229], v[12:15]
	v_add_u32_e32 v170, s62, v142
	ds_read_b128 v[162:165], v170 offset:256
	s_nop 0
	v_mfma_f32_16x16x32_bf16 v[8:11], v[158:161], v[226:229], v[8:11]
	ds_read_b128 v[170:173], v170 offset:2304
	global_load_lds_dwordx4 v[140:141], off
	v_mfma_f32_16x16x32_bf16 v[52:55], v[166:169], v[188:191], v[52:55]
	v_mfma_f32_16x16x32_bf16 v[48:51], v[180:183], v[188:191], v[48:51]
	v_mfma_f32_16x16x32_bf16 v[36:39], v[166:169], v[196:199], v[36:39]
	v_mfma_f32_16x16x32_bf16 v[32:35], v[180:183], v[196:199], v[32:35]
	v_mfma_f32_16x16x32_bf16 v[20:23], v[166:169], v[204:207], v[20:23]
	v_mfma_f32_16x16x32_bf16 v[16:19], v[180:183], v[204:207], v[16:19]
	v_mfma_f32_16x16x32_bf16 v[4:7], v[166:169], v[226:229], v[4:7]
	v_mfma_f32_16x16x32_bf16 v[0:3], v[180:183], v[226:229], v[0:3]
	s_add_i32 s46, s46, 2
	s_add_u32 s20, s20, 0x100
	s_addc_u32 s21, s21, 0
	s_add_u32 s44, s44, 0x100
	s_addc_u32 s45, s45, 0
	s_cmp_gt_u32 s46, 29
	s_cbranch_scc0 .Lpg_g9_loop
	s_waitcnt lgkmcnt(0)
	s_and_b64 vcc, exec, s[10:11]
	s_cbranch_vccz .LBB0_1029
	s_nop 0
.LBB0_1029:
	v_max_f32_e32 v120, v120, v120
	v_lshl_add_u32 v146, s41, 8, v129
	v_max_f32_e32 v120, 0, v120
	v_max_f32_e32 v121, v121, v121
	v_max_f32_e32 v122, v122, v122
	v_lshl_or_b32 v140, s40, 8, v143
	v_ashrrev_i32_e32 v147, 31, v146
	v_mul_f32_e32 v145, v120, v120
	v_max_f32_e32 v120, v125, v125
	v_max_f32_e32 v121, 0, v121
	v_max_f32_e32 v122, 0, v122
	v_ashrrev_i32_e32 v141, 31, v140
	v_lshlrev_b64 v[148:149], 14, v[146:147]
	v_max_f32_e32 v124, v124, v124
	v_max_f32_e32 v120, 0, v120
	v_mul_f32_e32 v125, v121, v121
	v_max_f32_e32 v121, v126, v126
	v_mul_f32_e32 v126, v122, v122
	v_max_f32_e32 v122, v127, v127
	v_max_f32_e32 v123, v123, v123
	v_lshl_add_u64 v[148:149], s[4:5], 0, v[148:149]
	v_lshlrev_b64 v[150:151], 1, v[140:141]
	v_max_f32_e32 v124, 0, v124
	v_mul_f32_e32 v120, v120, v120
	v_max_f32_e32 v121, 0, v121
	v_max_f32_e32 v122, 0, v122
	v_max_f32_e32 v123, 0, v123
	v_max_f32_e32 v112, v112, v112
	v_lshl_add_u64 v[140:141], v[148:149], 0, v[150:151]
	v_mul_f32_e32 v124, v124, v124
	v_mul_f32_e32 v121, v121, v121
	v_mul_f32_e32 v122, v122, v122
	v_mul_f32_e32 v123, v123, v123
	v_cvt_pk_bf16_f32 v120, v124, v120
	v_max_f32_e32 v112, 0, v112
	v_max_f32_e32 v113, v113, v113
	v_max_f32_e32 v114, v114, v114
	v_cvt_pk_bf16_f32 v121, v121, v122
	v_cvt_pk_bf16_f32 v122, v145, v125
	v_cvt_pk_bf16_f32 v123, v126, v123
	global_store_dwordx4 v[140:141], v[120:123], off
	v_max_f32_e32 v113, 0, v113
	v_max_f32_e32 v114, 0, v114
	v_mul_f32_e32 v120, v112, v112
	v_max_f32_e32 v112, v117, v117
	v_max_f32_e32 v116, v116, v116
	v_max_f32_e32 v112, 0, v112
	v_mul_f32_e32 v117, v113, v113
	v_max_f32_e32 v113, v118, v118
	v_mul_f32_e32 v118, v114, v114
	v_max_f32_e32 v114, v119, v119
	v_max_f32_e32 v115, v115, v115
	v_max_f32_e32 v116, 0, v116
	v_mul_f32_e32 v112, v112, v112
	v_max_f32_e32 v113, 0, v113
	v_max_f32_e32 v114, 0, v114
	v_max_f32_e32 v115, 0, v115
	v_mul_f32_e32 v116, v116, v116
	v_mul_f32_e32 v113, v113, v113
	v_mul_f32_e32 v114, v114, v114
	v_mul_f32_e32 v115, v115, v115
	v_cvt_pk_bf16_f32 v112, v116, v112
	v_max_f32_e32 v104, v104, v104
	v_cvt_pk_bf16_f32 v113, v113, v114
	v_cvt_pk_bf16_f32 v114, v120, v117
	v_cvt_pk_bf16_f32 v115, v118, v115
	global_store_dwordx4 v[140:141], v[112:115], off offset:256
	v_max_f32_e32 v104, 0, v104
	v_max_f32_e32 v105, v105, v105
	v_or_b32_e32 v112, 16, v146
	v_max_f32_e32 v106, v106, v106
	v_ashrrev_i32_e32 v113, 31, v112
	v_mul_f32_e32 v114, v104, v104
	v_max_f32_e32 v104, v109, v109
	v_max_f32_e32 v105, 0, v105
	v_max_f32_e32 v106, 0, v106
	v_lshlrev_b64 v[112:113], 14, v[112:113]
	v_max_f32_e32 v108, v108, v108
	v_max_f32_e32 v104, 0, v104
	v_mul_f32_e32 v109, v105, v105
	v_max_f32_e32 v105, v110, v110
	v_mul_f32_e32 v110, v106, v106
	v_max_f32_e32 v106, v111, v111
	v_max_f32_e32 v107, v107, v107
	v_lshl_add_u64 v[112:113], s[4:5], 0, v[112:113]
	v_max_f32_e32 v108, 0, v108
	v_mul_f32_e32 v104, v104, v104
	v_max_f32_e32 v105, 0, v105
	v_max_f32_e32 v106, 0, v106
	v_max_f32_e32 v107, 0, v107
	v_max_f32_e32 v96, v96, v96
	v_lshl_add_u64 v[112:113], v[112:113], 0, v[150:151]
	v_mul_f32_e32 v108, v108, v108
	v_mul_f32_e32 v105, v105, v105
	v_mul_f32_e32 v106, v106, v106
	v_mul_f32_e32 v107, v107, v107
	v_cvt_pk_bf16_f32 v104, v108, v104
	v_max_f32_e32 v96, 0, v96
	v_max_f32_e32 v97, v97, v97
	v_max_f32_e32 v98, v98, v98
	v_cvt_pk_bf16_f32 v105, v105, v106
	v_cvt_pk_bf16_f32 v106, v114, v109
	v_cvt_pk_bf16_f32 v107, v110, v107
	global_store_dwordx4 v[112:113], v[104:107], off
	v_max_f32_e32 v97, 0, v97
	v_max_f32_e32 v98, 0, v98
	v_mul_f32_e32 v104, v96, v96
	v_max_f32_e32 v96, v101, v101
	v_max_f32_e32 v100, v100, v100
	v_max_f32_e32 v96, 0, v96
	v_mul_f32_e32 v101, v97, v97
	v_max_f32_e32 v97, v102, v102
	v_mul_f32_e32 v102, v98, v98
	v_max_f32_e32 v98, v103, v103
	v_max_f32_e32 v99, v99, v99
	v_max_f32_e32 v100, 0, v100
	v_mul_f32_e32 v96, v96, v96
	v_max_f32_e32 v97, 0, v97
	v_max_f32_e32 v98, 0, v98
	v_max_f32_e32 v99, 0, v99
	v_mul_f32_e32 v100, v100, v100
	v_mul_f32_e32 v97, v97, v97
	v_mul_f32_e32 v98, v98, v98
	v_mul_f32_e32 v99, v99, v99
	v_cvt_pk_bf16_f32 v96, v100, v96
	v_max_f32_e32 v88, v88, v88
	v_cvt_pk_bf16_f32 v97, v97, v98
	v_cvt_pk_bf16_f32 v98, v104, v101
	v_cvt_pk_bf16_f32 v99, v102, v99
	global_store_dwordx4 v[112:113], v[96:99], off offset:256
	v_max_f32_e32 v88, 0, v88
	v_max_f32_e32 v89, v89, v89
	v_or_b32_e32 v96, 32, v146
	v_max_f32_e32 v90, v90, v90
	v_ashrrev_i32_e32 v97, 31, v96
	v_mul_f32_e32 v98, v88, v88
	v_max_f32_e32 v88, v93, v93
	v_max_f32_e32 v89, 0, v89
	v_max_f32_e32 v90, 0, v90
	v_lshlrev_b64 v[96:97], 14, v[96:97]
	v_max_f32_e32 v92, v92, v92
	v_max_f32_e32 v88, 0, v88
	v_mul_f32_e32 v93, v89, v89
	v_max_f32_e32 v89, v94, v94
	v_mul_f32_e32 v94, v90, v90
	v_max_f32_e32 v90, v95, v95
	v_max_f32_e32 v91, v91, v91
	v_lshl_add_u64 v[96:97], s[4:5], 0, v[96:97]
	v_max_f32_e32 v92, 0, v92
	v_mul_f32_e32 v88, v88, v88
	v_max_f32_e32 v89, 0, v89
	v_max_f32_e32 v90, 0, v90
	v_max_f32_e32 v91, 0, v91
	v_max_f32_e32 v80, v80, v80
	v_lshl_add_u64 v[96:97], v[96:97], 0, v[150:151]
	v_mul_f32_e32 v92, v92, v92
	v_mul_f32_e32 v89, v89, v89
	v_mul_f32_e32 v90, v90, v90
	v_mul_f32_e32 v91, v91, v91
	v_cvt_pk_bf16_f32 v88, v92, v88
	v_max_f32_e32 v80, 0, v80
	v_max_f32_e32 v81, v81, v81
	v_max_f32_e32 v82, v82, v82
	v_cvt_pk_bf16_f32 v89, v89, v90
	v_cvt_pk_bf16_f32 v90, v98, v93
	v_cvt_pk_bf16_f32 v91, v94, v91
	global_store_dwordx4 v[96:97], v[88:91], off
	v_max_f32_e32 v81, 0, v81
	v_max_f32_e32 v82, 0, v82
	v_mul_f32_e32 v88, v80, v80
	v_max_f32_e32 v80, v85, v85
	v_max_f32_e32 v84, v84, v84
	v_max_f32_e32 v80, 0, v80
	v_mul_f32_e32 v85, v81, v81
	v_max_f32_e32 v81, v86, v86
	v_mul_f32_e32 v86, v82, v82
	v_max_f32_e32 v82, v87, v87
	v_max_f32_e32 v83, v83, v83
	v_max_f32_e32 v84, 0, v84
	v_mul_f32_e32 v80, v80, v80
	v_max_f32_e32 v81, 0, v81
	v_max_f32_e32 v82, 0, v82
	v_max_f32_e32 v83, 0, v83
	v_mul_f32_e32 v84, v84, v84
	v_mul_f32_e32 v81, v81, v81
	v_mul_f32_e32 v82, v82, v82
	v_mul_f32_e32 v83, v83, v83
	v_cvt_pk_bf16_f32 v80, v84, v80
	v_max_f32_e32 v72, v72, v72
	v_cvt_pk_bf16_f32 v81, v81, v82
	v_cvt_pk_bf16_f32 v82, v88, v85
	v_cvt_pk_bf16_f32 v83, v86, v83
	global_store_dwordx4 v[96:97], v[80:83], off offset:256
	v_max_f32_e32 v72, 0, v72
	v_max_f32_e32 v73, v73, v73
	v_or_b32_e32 v80, 48, v146
	v_max_f32_e32 v74, v74, v74
	v_ashrrev_i32_e32 v81, 31, v80
	v_mul_f32_e32 v82, v72, v72
	v_max_f32_e32 v72, v77, v77
	v_max_f32_e32 v73, 0, v73
	v_max_f32_e32 v74, 0, v74
	v_lshlrev_b64 v[80:81], 14, v[80:81]
	v_max_f32_e32 v76, v76, v76
	v_max_f32_e32 v72, 0, v72
	v_mul_f32_e32 v77, v73, v73
	v_max_f32_e32 v73, v78, v78
	v_mul_f32_e32 v78, v74, v74
	v_max_f32_e32 v74, v79, v79
	v_max_f32_e32 v75, v75, v75
	v_lshl_add_u64 v[80:81], s[4:5], 0, v[80:81]
	v_max_f32_e32 v76, 0, v76
	v_mul_f32_e32 v72, v72, v72
	v_max_f32_e32 v73, 0, v73
	v_max_f32_e32 v74, 0, v74
	v_max_f32_e32 v75, 0, v75
	v_max_f32_e32 v64, v64, v64
	v_max_f32_e32 v65, v65, v65
	v_max_f32_e32 v66, v66, v66
	v_lshl_add_u64 v[80:81], v[80:81], 0, v[150:151]
	v_mul_f32_e32 v76, v76, v76
	v_mul_f32_e32 v73, v73, v73
	v_mul_f32_e32 v74, v74, v74
	v_mul_f32_e32 v75, v75, v75
	v_cvt_pk_bf16_f32 v72, v76, v72
	v_max_f32_e32 v64, 0, v64
	v_max_f32_e32 v65, 0, v65
	v_max_f32_e32 v66, 0, v66
	v_cvt_pk_bf16_f32 v73, v73, v74
	v_cvt_pk_bf16_f32 v74, v82, v77
	v_cvt_pk_bf16_f32 v75, v78, v75
	global_store_dwordx4 v[80:81], v[72:75], off
	v_max_f32_e32 v68, v68, v68
	v_max_f32_e32 v67, v67, v67
	v_mul_f32_e32 v72, v64, v64
	v_max_f32_e32 v64, v69, v69
	v_mul_f32_e32 v69, v65, v65
	v_max_f32_e32 v65, v70, v70
	v_mul_f32_e32 v70, v66, v66
	v_max_f32_e32 v66, v71, v71
	v_max_f32_e32 v64, 0, v64
	v_max_f32_e32 v65, 0, v65
	v_max_f32_e32 v66, 0, v66
	v_max_f32_e32 v68, 0, v68
	v_mul_f32_e32 v64, v64, v64
	v_mul_f32_e32 v65, v65, v65
	v_max_f32_e32 v67, 0, v67
	v_mul_f32_e32 v66, v66, v66
	v_max_f32_e32 v56, v56, v56
	v_mul_f32_e32 v68, v68, v68
	v_mul_f32_e32 v67, v67, v67
	v_cvt_pk_bf16_f32 v64, v68, v64
	v_cvt_pk_bf16_f32 v65, v65, v66
	v_cvt_pk_bf16_f32 v66, v72, v69
	v_max_f32_e32 v56, 0, v56
	v_max_f32_e32 v57, v57, v57
	v_max_f32_e32 v58, v58, v58
	v_cvt_pk_bf16_f32 v67, v70, v67
	global_store_dwordx4 v[80:81], v[64:67], off offset:256
	v_max_f32_e32 v60, v60, v60
	v_max_f32_e32 v57, 0, v57
	v_mul_f32_e32 v66, v56, v56
	v_max_f32_e32 v56, v61, v61
	v_max_f32_e32 v58, 0, v58
	v_max_f32_e32 v60, 0, v60
	v_max_f32_e32 v56, 0, v56
	v_mul_f32_e32 v61, v57, v57
	v_max_f32_e32 v57, v62, v62
	v_mul_f32_e32 v62, v58, v58
	v_max_f32_e32 v58, v63, v63
	v_mul_f32_e32 v60, v60, v60
	v_mul_f32_e32 v56, v56, v56
	v_max_f32_e32 v57, 0, v57
	v_max_f32_e32 v58, 0, v58
	v_max_f32_e32 v59, v59, v59
	s_mov_b32 s13, 0x200000
	v_mul_f32_e32 v57, v57, v57
	v_max_f32_e32 v59, 0, v59
	v_mul_f32_e32 v58, v58, v58
	v_cvt_pk_bf16_f32 v56, v60, v56
	v_add_co_u32_e32 v60, vcc, s13, v140
	v_max_f32_e32 v48, v48, v48
	v_max_f32_e32 v49, v49, v49
	v_max_f32_e32 v50, v50, v50
	v_mul_f32_e32 v59, v59, v59
	v_cvt_pk_bf16_f32 v57, v57, v58
	v_cvt_pk_bf16_f32 v58, v66, v61
	v_addc_co_u32_e32 v61, vcc, 0, v141, vcc
	v_max_f32_e32 v48, 0, v48
	v_max_f32_e32 v49, 0, v49
	v_max_f32_e32 v50, 0, v50
	v_cvt_pk_bf16_f32 v59, v62, v59
	global_store_dwordx4 v[60:61], v[56:59], off
	v_max_f32_e32 v52, v52, v52
	v_max_f32_e32 v51, v51, v51
	v_mul_f32_e32 v56, v48, v48
	v_max_f32_e32 v48, v53, v53
	v_mul_f32_e32 v53, v49, v49
	v_max_f32_e32 v49, v54, v54
	v_mul_f32_e32 v54, v50, v50
	v_max_f32_e32 v50, v55, v55
	v_max_f32_e32 v48, 0, v48
	v_max_f32_e32 v49, 0, v49
	v_max_f32_e32 v50, 0, v50
	s_mov_b64 s[20:21], 0x200000
	v_max_f32_e32 v52, 0, v52
	v_mul_f32_e32 v48, v48, v48
	v_mul_f32_e32 v49, v49, v49
	v_max_f32_e32 v51, 0, v51
	v_mul_f32_e32 v50, v50, v50
	v_max_f32_e32 v40, v40, v40
	v_lshl_add_u64 v[64:65], v[140:141], 0, s[20:21]
	v_mul_f32_e32 v52, v52, v52
	v_mul_f32_e32 v51, v51, v51
	v_cvt_pk_bf16_f32 v48, v52, v48
	v_cvt_pk_bf16_f32 v49, v49, v50
	v_cvt_pk_bf16_f32 v50, v56, v53
	v_max_f32_e32 v40, 0, v40
	v_max_f32_e32 v41, v41, v41
	v_max_f32_e32 v42, v42, v42
	v_cvt_pk_bf16_f32 v51, v54, v51
	global_store_dwordx4 v[64:65], v[48:51], off offset:256
	v_max_f32_e32 v44, v44, v44
	v_max_f32_e32 v41, 0, v41
	v_mul_f32_e32 v50, v40, v40
	v_max_f32_e32 v40, v45, v45
	v_max_f32_e32 v42, 0, v42
	v_max_f32_e32 v44, 0, v44
	v_max_f32_e32 v40, 0, v40
	v_mul_f32_e32 v45, v41, v41
	v_max_f32_e32 v41, v46, v46
	v_mul_f32_e32 v46, v42, v42
	v_max_f32_e32 v42, v47, v47
	v_mul_f32_e32 v44, v44, v44
	v_mul_f32_e32 v40, v40, v40
	v_max_f32_e32 v41, 0, v41
	v_max_f32_e32 v42, 0, v42
	v_max_f32_e32 v43, v43, v43
	s_mov_b32 s13, 0x240000
	v_mul_f32_e32 v41, v41, v41
	v_max_f32_e32 v43, 0, v43
	v_mul_f32_e32 v42, v42, v42
	v_cvt_pk_bf16_f32 v40, v44, v40
	v_add_co_u32_e32 v44, vcc, s13, v140
	v_max_f32_e32 v32, v32, v32
	v_max_f32_e32 v33, v33, v33
	v_max_f32_e32 v34, v34, v34
	v_mul_f32_e32 v43, v43, v43
	v_cvt_pk_bf16_f32 v41, v41, v42
	v_cvt_pk_bf16_f32 v42, v50, v45
	v_addc_co_u32_e32 v45, vcc, 0, v141, vcc
	v_max_f32_e32 v32, 0, v32
	v_max_f32_e32 v33, 0, v33
	v_max_f32_e32 v34, 0, v34
	v_cvt_pk_bf16_f32 v43, v46, v43
	global_store_dwordx4 v[44:45], v[40:43], off
	v_max_f32_e32 v36, v36, v36
	v_max_f32_e32 v35, v35, v35
	v_mul_f32_e32 v40, v32, v32
	v_max_f32_e32 v32, v37, v37
	v_mul_f32_e32 v37, v33, v33
	v_max_f32_e32 v33, v38, v38
	v_mul_f32_e32 v38, v34, v34
	v_max_f32_e32 v34, v39, v39
	v_max_f32_e32 v32, 0, v32
	v_max_f32_e32 v33, 0, v33
	v_max_f32_e32 v34, 0, v34
	s_mov_b64 s[20:21], 0x240000
	v_max_f32_e32 v36, 0, v36
	v_mul_f32_e32 v32, v32, v32
	v_mul_f32_e32 v33, v33, v33
	v_max_f32_e32 v35, 0, v35
	v_mul_f32_e32 v34, v34, v34
	v_max_f32_e32 v24, v24, v24
	v_lshl_add_u64 v[48:49], v[140:141], 0, s[20:21]
	v_mul_f32_e32 v36, v36, v36
	v_mul_f32_e32 v35, v35, v35
	v_cvt_pk_bf16_f32 v32, v36, v32
	v_cvt_pk_bf16_f32 v33, v33, v34
	v_cvt_pk_bf16_f32 v34, v40, v37
	v_max_f32_e32 v24, 0, v24
	v_max_f32_e32 v25, v25, v25
	v_max_f32_e32 v26, v26, v26
	v_cvt_pk_bf16_f32 v35, v38, v35
	global_store_dwordx4 v[48:49], v[32:35], off offset:256
	v_max_f32_e32 v28, v28, v28
	v_max_f32_e32 v25, 0, v25
	v_mul_f32_e32 v34, v24, v24
	v_max_f32_e32 v24, v29, v29
	v_max_f32_e32 v26, 0, v26
	v_max_f32_e32 v28, 0, v28
	v_max_f32_e32 v24, 0, v24
	v_mul_f32_e32 v29, v25, v25
	v_max_f32_e32 v25, v30, v30
	v_mul_f32_e32 v30, v26, v26
	v_max_f32_e32 v26, v31, v31
	v_mul_f32_e32 v28, v28, v28
	v_mul_f32_e32 v24, v24, v24
	v_max_f32_e32 v25, 0, v25
	v_max_f32_e32 v26, 0, v26
	v_max_f32_e32 v27, v27, v27
	s_mov_b32 s13, 0x280000
	v_mul_f32_e32 v25, v25, v25
	v_max_f32_e32 v27, 0, v27
	v_mul_f32_e32 v26, v26, v26
	v_cvt_pk_bf16_f32 v24, v28, v24
	v_add_co_u32_e32 v28, vcc, s13, v140
	v_max_f32_e32 v16, v16, v16
	v_max_f32_e32 v17, v17, v17
	v_max_f32_e32 v18, v18, v18
	v_mul_f32_e32 v27, v27, v27
	v_cvt_pk_bf16_f32 v25, v25, v26
	v_cvt_pk_bf16_f32 v26, v34, v29
	v_addc_co_u32_e32 v29, vcc, 0, v141, vcc
	v_max_f32_e32 v16, 0, v16
	v_max_f32_e32 v17, 0, v17
	v_max_f32_e32 v18, 0, v18
	v_cvt_pk_bf16_f32 v27, v30, v27
	global_store_dwordx4 v[28:29], v[24:27], off
	v_max_f32_e32 v20, v20, v20
	v_max_f32_e32 v19, v19, v19
	v_mul_f32_e32 v24, v16, v16
	v_max_f32_e32 v16, v21, v21
	v_mul_f32_e32 v21, v17, v17
	v_max_f32_e32 v17, v22, v22
	v_mul_f32_e32 v22, v18, v18
	v_max_f32_e32 v18, v23, v23
	v_max_f32_e32 v16, 0, v16
	v_max_f32_e32 v17, 0, v17
	v_max_f32_e32 v18, 0, v18
	s_mov_b64 s[20:21], 0x280000
	v_max_f32_e32 v20, 0, v20
	v_mul_f32_e32 v16, v16, v16
	v_mul_f32_e32 v17, v17, v17
	v_max_f32_e32 v19, 0, v19
	v_mul_f32_e32 v18, v18, v18
	v_max_f32_e32 v8, v8, v8
	v_lshl_add_u64 v[32:33], v[140:141], 0, s[20:21]
	v_mul_f32_e32 v20, v20, v20
	v_mul_f32_e32 v19, v19, v19
	v_cvt_pk_bf16_f32 v16, v20, v16
	v_cvt_pk_bf16_f32 v17, v17, v18
	v_cvt_pk_bf16_f32 v18, v24, v21
	v_max_f32_e32 v8, 0, v8
	v_max_f32_e32 v9, v9, v9
	v_max_f32_e32 v10, v10, v10
	v_cvt_pk_bf16_f32 v19, v22, v19
	global_store_dwordx4 v[32:33], v[16:19], off offset:256
	v_max_f32_e32 v12, v12, v12
	v_max_f32_e32 v9, 0, v9
	v_mul_f32_e32 v18, v8, v8
	v_max_f32_e32 v8, v13, v13
	v_max_f32_e32 v10, 0, v10
	v_max_f32_e32 v12, 0, v12
	v_max_f32_e32 v8, 0, v8
	v_mul_f32_e32 v13, v9, v9
	v_max_f32_e32 v9, v14, v14
	v_mul_f32_e32 v14, v10, v10
	v_max_f32_e32 v10, v15, v15
	v_mul_f32_e32 v12, v12, v12
	v_mul_f32_e32 v8, v8, v8
	v_max_f32_e32 v9, 0, v9
	v_max_f32_e32 v10, 0, v10
	v_max_f32_e32 v11, v11, v11
	s_mov_b32 s13, 0x2c0000
	v_mul_f32_e32 v9, v9, v9
	v_max_f32_e32 v11, 0, v11
	v_mul_f32_e32 v10, v10, v10
	v_cvt_pk_bf16_f32 v8, v12, v8
	v_add_co_u32_e32 v12, vcc, s13, v140
	v_max_f32_e32 v0, v0, v0
	v_max_f32_e32 v1, v1, v1
	v_max_f32_e32 v2, v2, v2
	v_mul_f32_e32 v11, v11, v11
	v_cvt_pk_bf16_f32 v9, v9, v10
	v_cvt_pk_bf16_f32 v10, v18, v13
	v_addc_co_u32_e32 v13, vcc, 0, v141, vcc
	v_max_f32_e32 v0, 0, v0
	v_max_f32_e32 v1, 0, v1
	v_max_f32_e32 v2, 0, v2
	v_cvt_pk_bf16_f32 v11, v14, v11
	global_store_dwordx4 v[12:13], v[8:11], off
	v_max_f32_e32 v3, v3, v3
	s_mov_b64 s[20:21], 0x2c0000
	v_mul_f32_e32 v8, v0, v0
	v_max_f32_e32 v0, v5, v5
	v_mul_f32_e32 v5, v1, v1
	v_max_f32_e32 v1, v6, v6
	v_mul_f32_e32 v6, v2, v2
	v_max_f32_e32 v2, v7, v7
	v_max_f32_e32 v4, v4, v4
	v_max_f32_e32 v0, 0, v0
	v_max_f32_e32 v1, 0, v1
	v_max_f32_e32 v2, 0, v2
	v_max_f32_e32 v3, 0, v3
	v_lshl_add_u64 v[16:17], v[140:141], 0, s[20:21]
	v_max_f32_e32 v4, 0, v4
	v_mul_f32_e32 v0, v0, v0
	v_mul_f32_e32 v1, v1, v1
	v_mul_f32_e32 v2, v2, v2
	v_mul_f32_e32 v3, v3, v3
	s_andn2_b64 vcc, exec, s[0:1]
	s_mov_b64 s[0:1], -1
	v_mul_f32_e32 v4, v4, v4
	v_cvt_pk_bf16_f32 v0, v4, v0
	v_cvt_pk_bf16_f32 v1, v1, v2
	v_cvt_pk_bf16_f32 v2, v8, v5
	v_cvt_pk_bf16_f32 v3, v6, v3
	global_store_dwordx4 v[16:17], v[0:3], off offset:256
	s_cbranch_vccnz .LBB0_1018
	s_andn2_b64 vcc, exec, s[2:3]
	s_cbranch_vccnz .LBB0_1017
	s_nop 0
	s_branch .LBB0_1017

.LBB0_1107:
	s_mov_b64 s[4:5], s[94:95]
	s_mov_b64 s[2:3], s[94:95]
	s_mov_b64 s[0:1], s[94:95]
	s_waitcnt vmcnt(0)
	v_mov_b32_e32 v14, v176
	s_and_b64 vcc, exec, s[8:9]
	v_readfirstlane_b32 s8, v14
	s_cbranch_vccnz .LBB0_1127
	v_lshlrev_b32_e32 v0, 4, v14
	v_add_u32_e32 v1, 0x2000, v0
	v_ashrrev_i32_e32 v2, 31, v1
	v_lshrrev_b32_e32 v2, 22, v2
	v_add_u32_e32 v2, v1, v2
	v_ashrrev_i32_e32 v8, 10, v2
	v_mul_i32_i24_e32 v2, 0x400, v8
	s_load_dwordx2 s[4:5], s[4:5], 0xc0
	s_nop 0
	s_load_dwordx2 s[2:3], s[2:3], 0xc0
	v_sub_u32_e32 v1, v1, v2
	v_lshrrev_b32_e32 v2, 4, v1
	v_bitop3_b32 v1, v2, v1, 32 bitop3:0x6c
	v_ashrrev_i32_e32 v2, 31, v1
	s_waitcnt lgkmcnt(0)
	s_add_u32 s24, s4, 0x35200000
	v_lshrrev_b32_e32 v2, 26, v2
	s_mul_i32 s9, s82, 0x5d00000
	s_addc_u32 s25, s5, 0
	v_add_u32_e32 v2, v1, v2
	v_lshlrev_b32_e32 v3, 3, v8
	s_add_u32 s2, s2, s9
	v_ashrrev_i32_e32 v9, 6, v2
	v_and_b32_e32 v3, -16, v3
	s_addc_u32 s3, s3, 0
	v_add_u32_e32 v3, v9, v3
	s_add_u32 s26, s2, 0x4100000
	v_and_b32_e32 v4, 3, v9
	s_mov_b32 s2, 0x3ffe0
	v_lshrrev_b32_e32 v5, 2, v3
	v_lshlrev_b32_e32 v6, 1, v3
	v_and_b32_e32 v2, 0xc0, v2
	v_and_or_b32 v4, v3, s2, v4
	v_and_b32_e32 v5, 4, v5
	v_and_b32_e32 v6, 24, v6
	v_sub_u32_e32 v1, v1, v2
	v_or3_b32 v4, v4, v5, v6
	v_lshlrev_b32_e32 v5, 5, v8
	v_ashrrev_i16_sdwa v1, v177, sext(v1) dst_sel:DWORD dst_unused:UNUSED_PAD src0_sel:DWORD src1_sel:BYTE_0
	v_and_b32_e32 v5, 32, v5
	v_bfe_i32 v10, v1, 0, 16
	v_add_lshl_u32 v1, v5, v10, 1
	v_lshl_add_u32 v130, v4, 14, v1
	v_lshl_add_u32 v132, v3, 14, v1
	v_bfe_i32 v1, v14, 27, 1
	v_lshrrev_b32_e32 v1, 22, v1
	v_add_u32_e32 v1, v0, v1
	v_and_b32_e32 v1, 0xfffffc00, v1
	v_sub_u32_e32 v0, v0, v1
	v_lshrrev_b32_e32 v1, 4, v0
	v_ashrrev_i32_e32 v2, 31, v14
	v_bitop3_b32 v0, v1, v0, 32 bitop3:0x6c
	v_lshrrev_b32_e32 v2, 26, v2
	v_ashrrev_i32_e32 v1, 31, v0
	v_add_u32_e32 v2, v14, v2
	v_lshrrev_b32_e32 v1, 26, v1
	v_ashrrev_i32_e32 v12, 6, v2
	v_add_u32_e32 v1, v0, v1
	v_lshlrev_b32_e32 v2, 3, v12
	v_ashrrev_i32_e32 v11, 6, v1
	v_and_b32_e32 v2, -16, v2
	v_add_u32_e32 v2, v11, v2
	v_and_b32_e32 v3, 3, v11
	v_lshrrev_b32_e32 v4, 2, v2
	v_lshlrev_b32_e32 v5, 1, v2
	v_and_b32_e32 v1, 0xc0, v1
	s_addc_u32 s27, s3, 0
	s_ashr_i32 s9, s8, 6
	v_and_or_b32 v3, v2, s2, v3
	v_and_b32_e32 v4, 4, v4
	v_and_b32_e32 v5, 24, v5
	v_sub_u32_e32 v0, v0, v1
	s_ashr_i32 s10, s8, 8
	s_lshl_b32 s28, s9, 10
	v_or3_b32 v3, v3, v4, v5
	v_lshlrev_b32_e32 v4, 5, v12
	v_ashrrev_i16_sdwa v0, v177, sext(v0) dst_sel:DWORD dst_unused:UNUSED_PAD src0_sel:DWORD src1_sel:BYTE_0
	v_readlane_b32 s2, v253, 36
	v_and_b32_e32 v4, 32, v4
	v_bfe_i32 v13, v0, 0, 16
	v_readlane_b32 s3, v253, 37
	s_add_u32 s20, s26, s2
	v_add_lshl_u32 v0, v4, v13, 1
	s_addc_u32 s21, s27, s3
	s_add_i32 s29, s28, 0x100
	v_lshl_add_u32 v178, v3, 14, v0
	s_add_i32 m0, s29, 0x10000
	v_lshl_add_u32 v134, v2, 14, v0
	global_load_lds_dwordx4 v178, s[20:21]
	s_add_i32 m0, s29, 0x12000
	s_add_u32 s2, s20, 0x200000
	global_load_lds_dwordx4 v130, s[20:21]
	s_addc_u32 s3, s21, 0
	s_add_i32 m0, s29, 0x14000
	s_load_dwordx2 s[0:1], s[0:1], 0xc0
	global_load_lds_dwordx4 v178, s[2:3]
	s_add_i32 m0, s29, 0x16000
	v_mov_b32_e32 v131, v179
	global_load_lds_dwordx4 v130, s[2:3]
	v_readlane_b32 s2, v254, 7
	v_readlane_b32 s3, v254, 8
	s_add_u32 s18, s24, s2
	s_addc_u32 s19, s25, s3
	s_add_i32 s30, s29, 0x2000
	s_mov_b32 m0, s29
	s_add_u32 s2, s18, 0x200000
	global_load_lds_dwordx4 v134, s[18:19]
	s_mov_b32 m0, s30
	s_addc_u32 s3, s19, 0
	s_add_i32 s31, s29, 0x4000
	global_load_lds_dwordx4 v132, s[18:19]
	s_mov_b32 m0, s31
	s_add_i32 s34, s29, 0x6000
	global_load_lds_dwordx4 v134, s[2:3]
	s_mov_b32 m0, s34
	v_mov_b32_e32 v135, v179
	global_load_lds_dwordx4 v132, s[2:3]
	v_mov_b32_e32 v133, v179
	s_cmp_eq_u32 s10, 1
	v_lshl_add_u64 v[6:7], s[20:21], 0, v[178:179]
	v_lshl_add_u64 v[4:5], s[20:21], 0, v[130:131]
	v_lshl_add_u64 v[0:1], s[18:19], 0, v[134:135]
	s_cselect_b64 s[2:3], -1, 0
	s_cmp_lg_u32 s10, 1
	v_lshl_add_u64 v[2:3], s[18:19], 0, v[132:133]
	s_cbranch_scc1 .LBB0_1110
	s_nop 0

.Lpg_g10_loop:
	s_waitcnt lgkmcnt(6)
	v_mfma_f32_16x16x32_bf16 v[124:127], v[146:149], v[184:187], v[124:127]
	ds_read_b128 v[188:191], v144 offset:1024
	s_add_u32 s20, s18, 0xffe00080
	s_waitcnt lgkmcnt(6)
	v_mfma_f32_16x16x32_bf16 v[120:123], v[154:157], v[184:187], v[120:123]
	v_add_u32_e32 v158, s93, v142
	ds_read_b128 v[150:153], v158 offset:1280
	s_addc_u32 s21, s19, -1
	s_waitcnt lgkmcnt(6)
	v_mfma_f32_16x16x32_bf16 v[116:119], v[146:149], v[192:195], v[116:119]
	ds_read_b128 v[158:161], v158 offset:3328
	s_add_i32 s45, s93, 0x100
	v_mfma_f32_16x16x32_bf16 v[108:111], v[154:157], v[192:195], v[108:111]
	ds_read_b128 v[196:199], v144 offset:3072
	s_cmpk_eq_i32 s44, 0x7c
	s_waitcnt lgkmcnt(7)
	v_mfma_f32_16x16x32_bf16 v[100:103], v[146:149], v[200:203], v[100:103]
	ds_read_b128 v[204:207], v144 offset:5120
	s_cselect_b32 s23, s13, s21
	v_mfma_f32_16x16x32_bf16 v[92:95], v[154:157], v[200:203], v[92:95]
	ds_read_b128 v[226:229], v144 offset:7168
	s_cselect_b32 s22, s40, s20
	s_waitcnt lgkmcnt(8)
	v_mfma_f32_16x16x32_bf16 v[84:87], v[146:149], v[208:211], v[84:87]
	v_add_u32_e32 v180, s62, v142
	ds_read_b128 v[166:169], v180 offset:1280
	s_cselect_b32 s21, s11, s43
	v_mfma_f32_16x16x32_bf16 v[76:79], v[154:157], v[208:211], v[76:79]
	ds_read_b128 v[180:183], v180 offset:3328
	s_cselect_b32 s20, s41, s42
	s_waitcnt lgkmcnt(9)
	v_mfma_f32_16x16x32_bf16 v[112:115], v[162:165], v[184:187], v[112:115]
	s_add_i32 s49, s62, 0x100
	s_waitcnt lgkmcnt(8)
	v_mfma_f32_16x16x32_bf16 v[104:107], v[170:173], v[184:187], v[104:107]
	s_add_i32 m0, s29, 0xc000
	v_mfma_f32_16x16x32_bf16 v[96:99], v[162:165], v[192:195], v[96:99]
	s_nop 0
	v_mfma_f32_16x16x32_bf16 v[88:91], v[170:173], v[192:195], v[88:91]
	global_load_lds_dwordx4 v136, s[18:19]
	v_mfma_f32_16x16x32_bf16 v[80:83], v[162:165], v[200:203], v[80:83]
	s_add_i32 m0, s29, 0xe000
	v_mfma_f32_16x16x32_bf16 v[72:75], v[170:173], v[200:203], v[72:75]
	s_nop 0
	v_mfma_f32_16x16x32_bf16 v[68:71], v[162:165], v[208:211], v[68:71]
	global_load_lds_dwordx4 v138, s[18:19]
	v_mfma_f32_16x16x32_bf16 v[64:67], v[170:173], v[208:211], v[64:67]
	s_waitcnt lgkmcnt(0)
	s_waitcnt vmcnt(8)
	s_barrier
	v_mfma_f32_16x16x32_bf16 v[124:127], v[150:153], v[188:191], v[124:127]
	ds_read_b128 v[184:187], v144 offset:16384
	s_add_i32 s45, s45, s28
	v_mfma_f32_16x16x32_bf16 v[120:123], v[158:161], v[188:191], v[120:123]
	ds_read_b128 v[192:195], v144 offset:18432
	v_lshl_add_u64 v[140:141], s[20:21], 0, v[178:179]
	v_mfma_f32_16x16x32_bf16 v[116:119], v[150:153], v[196:199], v[116:119]
	ds_read_b128 v[200:203], v144 offset:20480
	s_mov_b32 m0, s45
	v_mfma_f32_16x16x32_bf16 v[108:111], v[158:161], v[196:199], v[108:111]
	ds_read_b128 v[208:211], v144 offset:22528
	s_nop 0
	v_mfma_f32_16x16x32_bf16 v[100:103], v[150:153], v[204:207], v[100:103]
	global_load_lds_dwordx4 v[140:141], off
	v_mfma_f32_16x16x32_bf16 v[92:95], v[158:161], v[204:207], v[92:95]
	s_add_i32 m0, s45, 0x2000
	v_mfma_f32_16x16x32_bf16 v[84:87], v[150:153], v[226:229], v[84:87]
	s_add_u32 s46, s20, 0x200000
	v_mfma_f32_16x16x32_bf16 v[76:79], v[158:161], v[226:229], v[76:79]
	v_lshl_add_u64 v[174:175], s[20:21], 0, v[130:131]
	v_mfma_f32_16x16x32_bf16 v[112:115], v[166:169], v[188:191], v[112:115]
	s_addc_u32 s47, s21, 0
	v_mfma_f32_16x16x32_bf16 v[104:107], v[180:183], v[188:191], v[104:107]
	s_add_i32 s45, s49, s28
	v_mfma_f32_16x16x32_bf16 v[96:99], v[166:169], v[196:199], v[96:99]
	global_load_lds_dwordx4 v[174:175], off
	v_mfma_f32_16x16x32_bf16 v[88:91], v[180:183], v[196:199], v[88:91]
	s_mov_b32 m0, s45
	v_mfma_f32_16x16x32_bf16 v[80:83], v[166:169], v[204:207], v[80:83]
	v_lshl_add_u64 v[230:231], s[22:23], 0, v[132:133]
	v_mfma_f32_16x16x32_bf16 v[72:75], v[180:183], v[204:207], v[72:75]
	global_load_lds_dwordx4 v178, s[46:47]
	v_mfma_f32_16x16x32_bf16 v[68:71], v[166:169], v[226:229], v[68:71]
	s_add_i32 m0, s45, 0x2000
	v_mfma_f32_16x16x32_bf16 v[64:67], v[180:183], v[226:229], v[64:67]
	s_nop 0
	s_waitcnt lgkmcnt(3)
	v_mfma_f32_16x16x32_bf16 v[60:63], v[146:149], v[184:187], v[60:63]
	ds_read_b128 v[188:191], v144 offset:17408
	global_load_lds_dwordx4 v130, s[46:47]
	v_mfma_f32_16x16x32_bf16 v[56:59], v[154:157], v[184:187], v[56:59]
	ds_read_b128 v[196:199], v144 offset:19456
	s_waitcnt lgkmcnt(4)
	v_mfma_f32_16x16x32_bf16 v[52:55], v[146:149], v[192:195], v[52:55]
	ds_read_b128 v[204:207], v144 offset:21504
	v_mfma_f32_16x16x32_bf16 v[44:47], v[154:157], v[192:195], v[44:47]
	ds_read_b128 v[226:229], v144 offset:23552
	s_waitcnt lgkmcnt(5)
	v_mfma_f32_16x16x32_bf16 v[36:39], v[146:149], v[200:203], v[36:39]
	v_mfma_f32_16x16x32_bf16 v[28:31], v[154:157], v[200:203], v[28:31]
	s_waitcnt lgkmcnt(4)
	v_mfma_f32_16x16x32_bf16 v[20:23], v[146:149], v[208:211], v[20:23]
	v_mfma_f32_16x16x32_bf16 v[12:15], v[154:157], v[208:211], v[12:15]
	v_mfma_f32_16x16x32_bf16 v[48:51], v[162:165], v[184:187], v[48:51]
	v_mfma_f32_16x16x32_bf16 v[40:43], v[170:173], v[184:187], v[40:43]
	v_mfma_f32_16x16x32_bf16 v[32:35], v[162:165], v[192:195], v[32:35]
	v_mfma_f32_16x16x32_bf16 v[24:27], v[170:173], v[192:195], v[24:27]
	v_mfma_f32_16x16x32_bf16 v[16:19], v[162:165], v[200:203], v[16:19]
	v_mfma_f32_16x16x32_bf16 v[8:11], v[170:173], v[200:203], v[8:11]
	v_mfma_f32_16x16x32_bf16 v[4:7], v[162:165], v[208:211], v[4:7]
	v_mfma_f32_16x16x32_bf16 v[0:3], v[170:173], v[208:211], v[0:3]
	s_waitcnt lgkmcnt(0)
	s_waitcnt vmcnt(6)
	s_barrier
	v_mfma_f32_16x16x32_bf16 v[60:63], v[150:153], v[188:191], v[60:63]
	ds_read_b128 v[184:187], v144 offset:32768
	v_lshl_add_u64 v[212:213], s[22:23], 0, v[134:135]
	v_mfma_f32_16x16x32_bf16 v[56:59], v[158:161], v[188:191], v[56:59]
	v_add_u32_e32 v154, s63, v142
	ds_read_b128 v[146:149], v154 offset:256
	s_mov_b32 m0, s29
	v_mfma_f32_16x16x32_bf16 v[52:55], v[150:153], v[196:199], v[52:55]
	ds_read_b128 v[154:157], v154 offset:2304
	s_nop 0
	v_mfma_f32_16x16x32_bf16 v[44:47], v[158:161], v[196:199], v[44:47]
	ds_read_b128 v[192:195], v144 offset:34816
	global_load_lds_dwordx4 v[212:213], off
	v_mfma_f32_16x16x32_bf16 v[36:39], v[150:153], v[204:207], v[36:39]
	ds_read_b128 v[200:203], v144 offset:36864
	s_mov_b32 m0, s30
	v_mfma_f32_16x16x32_bf16 v[28:31], v[158:161], v[204:207], v[28:31]
	ds_read_b128 v[208:211], v144 offset:38912
	s_nop 0
	v_mfma_f32_16x16x32_bf16 v[20:23], v[150:153], v[226:229], v[20:23]
	v_add_u32_e32 v170, s75, v142
	ds_read_b128 v[162:165], v170 offset:256
	global_load_lds_dwordx4 v[230:231], off
	v_mfma_f32_16x16x32_bf16 v[12:15], v[158:161], v[226:229], v[12:15]
	ds_read_b128 v[170:173], v170 offset:2304
	s_add_i32 s45, s63, 0x100
	v_mfma_f32_16x16x32_bf16 v[48:51], v[166:169], v[188:191], v[48:51]
	s_add_i32 s46, s75, 0x100
	v_mfma_f32_16x16x32_bf16 v[40:43], v[180:183], v[188:191], v[40:43]
	s_add_u32 s22, s22, 0x200000
	v_mfma_f32_16x16x32_bf16 v[32:35], v[166:169], v[196:199], v[32:35]
	s_addc_u32 s23, s23, 0
	v_mfma_f32_16x16x32_bf16 v[24:27], v[180:183], v[196:199], v[24:27]
	s_mov_b32 m0, s31
	v_mfma_f32_16x16x32_bf16 v[16:19], v[166:169], v[204:207], v[16:19]
	s_nop 0
	v_mfma_f32_16x16x32_bf16 v[8:11], v[180:183], v[204:207], v[8:11]
	global_load_lds_dwordx4 v134, s[22:23]
	v_mfma_f32_16x16x32_bf16 v[4:7], v[166:169], v[226:229], v[4:7]
	s_mov_b32 m0, s34
	v_mfma_f32_16x16x32_bf16 v[0:3], v[180:183], v[226:229], v[0:3]
	s_nop 0
	s_waitcnt lgkmcnt(6)
	v_mfma_f32_16x16x32_bf16 v[124:127], v[146:149], v[184:187], v[124:127]
	ds_read_b128 v[188:191], v144 offset:33792
	global_load_lds_dwordx4 v132, s[22:23]
	s_waitcnt lgkmcnt(6)
	v_mfma_f32_16x16x32_bf16 v[120:123], v[154:157], v[184:187], v[120:123]
	v_add_u32_e32 v158, s63, v142
	ds_read_b128 v[150:153], v158 offset:1280
	s_waitcnt lgkmcnt(6)
	v_mfma_f32_16x16x32_bf16 v[116:119], v[146:149], v[192:195], v[116:119]
	ds_read_b128 v[158:161], v158 offset:3328
	v_mfma_f32_16x16x32_bf16 v[108:111], v[154:157], v[192:195], v[108:111]
	ds_read_b128 v[196:199], v144 offset:35840
	s_waitcnt lgkmcnt(7)
	v_mfma_f32_16x16x32_bf16 v[100:103], v[146:149], v[200:203], v[100:103]
	ds_read_b128 v[204:207], v144 offset:37888
	v_mfma_f32_16x16x32_bf16 v[92:95], v[154:157], v[200:203], v[92:95]
	ds_read_b128 v[226:229], v144 offset:39936
	s_waitcnt lgkmcnt(8)
	v_mfma_f32_16x16x32_bf16 v[84:87], v[146:149], v[208:211], v[84:87]
	v_add_u32_e32 v180, s75, v142
	ds_read_b128 v[166:169], v180 offset:1280
	v_mfma_f32_16x16x32_bf16 v[76:79], v[154:157], v[208:211], v[76:79]
	ds_read_b128 v[180:183], v180 offset:3328
	s_waitcnt lgkmcnt(9)
	v_mfma_f32_16x16x32_bf16 v[112:115], v[162:165], v[184:187], v[112:115]
	s_waitcnt lgkmcnt(8)
	v_mfma_f32_16x16x32_bf16 v[104:107], v[170:173], v[184:187], v[104:107]
	v_mfma_f32_16x16x32_bf16 v[96:99], v[162:165], v[192:195], v[96:99]
	v_mfma_f32_16x16x32_bf16 v[88:91], v[170:173], v[192:195], v[88:91]
	v_mfma_f32_16x16x32_bf16 v[80:83], v[162:165], v[200:203], v[80:83]
	v_mfma_f32_16x16x32_bf16 v[72:75], v[170:173], v[200:203], v[72:75]
	v_mfma_f32_16x16x32_bf16 v[68:71], v[162:165], v[208:211], v[68:71]
	v_mfma_f32_16x16x32_bf16 v[64:67], v[170:173], v[208:211], v[64:67]
	s_waitcnt lgkmcnt(0)
	s_waitcnt vmcnt(8)
	s_barrier
	v_mfma_f32_16x16x32_bf16 v[124:127], v[150:153], v[188:191], v[124:127]
	ds_read_b128 v[184:187], v144 offset:49152
	s_add_i32 s22, s45, s28
	v_mfma_f32_16x16x32_bf16 v[120:123], v[158:161], v[188:191], v[120:123]
	ds_read_b128 v[192:195], v144 offset:51200
	v_lshl_add_u64 v[140:141], v[140:141], 0, s[78:79]
	v_mfma_f32_16x16x32_bf16 v[116:119], v[150:153], v[196:199], v[116:119]
	ds_read_b128 v[200:203], v144 offset:53248
	s_mov_b32 m0, s22
	v_mfma_f32_16x16x32_bf16 v[108:111], v[158:161], v[196:199], v[108:111]
	ds_read_b128 v[208:211], v144 offset:55296
	s_nop 0
	v_mfma_f32_16x16x32_bf16 v[100:103], v[150:153], v[204:207], v[100:103]
	global_load_lds_dwordx4 v[140:141], off
	v_mfma_f32_16x16x32_bf16 v[92:95], v[158:161], v[204:207], v[92:95]
	s_add_i32 m0, s22, 0x2000
	v_mfma_f32_16x16x32_bf16 v[84:87], v[150:153], v[226:229], v[84:87]
	s_add_u32 s20, s20, 0x200080
	v_mfma_f32_16x16x32_bf16 v[76:79], v[158:161], v[226:229], v[76:79]
	v_lshl_add_u64 v[140:141], v[174:175], 0, s[78:79]
	v_mfma_f32_16x16x32_bf16 v[112:115], v[166:169], v[188:191], v[112:115]
	s_addc_u32 s21, s21, 0
	v_mfma_f32_16x16x32_bf16 v[104:107], v[180:183], v[188:191], v[104:107]
	s_add_i32 s22, s46, s28
	v_mfma_f32_16x16x32_bf16 v[96:99], v[166:169], v[196:199], v[96:99]
	global_load_lds_dwordx4 v[140:141], off
	v_mfma_f32_16x16x32_bf16 v[88:91], v[180:183], v[196:199], v[88:91]
	s_mov_b32 m0, s22
	v_mfma_f32_16x16x32_bf16 v[80:83], v[166:169], v[204:207], v[80:83]
	s_nop 0
	v_mfma_f32_16x16x32_bf16 v[72:75], v[180:183], v[204:207], v[72:75]
	global_load_lds_dwordx4 v178, s[20:21]
	v_mfma_f32_16x16x32_bf16 v[68:71], v[166:169], v[226:229], v[68:71]
	s_add_i32 m0, s22, 0x2000
	v_mfma_f32_16x16x32_bf16 v[64:67], v[180:183], v[226:229], v[64:67]
	s_nop 0
	s_waitcnt lgkmcnt(3)
	v_mfma_f32_16x16x32_bf16 v[60:63], v[146:149], v[184:187], v[60:63]
	ds_read_b128 v[188:191], v144 offset:50176
	global_load_lds_dwordx4 v130, s[20:21]
	v_mfma_f32_16x16x32_bf16 v[56:59], v[154:157], v[184:187], v[56:59]
	ds_read_b128 v[196:199], v144 offset:52224
	s_waitcnt lgkmcnt(4)
	v_mfma_f32_16x16x32_bf16 v[52:55], v[146:149], v[192:195], v[52:55]
	ds_read_b128 v[204:207], v144 offset:54272
	v_mfma_f32_16x16x32_bf16 v[44:47], v[154:157], v[192:195], v[44:47]
	ds_read_b128 v[226:229], v144 offset:56320
	s_waitcnt lgkmcnt(5)
	v_mfma_f32_16x16x32_bf16 v[36:39], v[146:149], v[200:203], v[36:39]
	v_mfma_f32_16x16x32_bf16 v[28:31], v[154:157], v[200:203], v[28:31]
	s_waitcnt lgkmcnt(4)
	v_mfma_f32_16x16x32_bf16 v[20:23], v[146:149], v[208:211], v[20:23]
	v_mfma_f32_16x16x32_bf16 v[12:15], v[154:157], v[208:211], v[12:15]
	v_mfma_f32_16x16x32_bf16 v[48:51], v[162:165], v[184:187], v[48:51]
	v_mfma_f32_16x16x32_bf16 v[40:43], v[170:173], v[184:187], v[40:43]
	v_mfma_f32_16x16x32_bf16 v[32:35], v[162:165], v[192:195], v[32:35]
	v_mfma_f32_16x16x32_bf16 v[24:27], v[170:173], v[192:195], v[24:27]
	v_mfma_f32_16x16x32_bf16 v[16:19], v[162:165], v[200:203], v[16:19]
	v_mfma_f32_16x16x32_bf16 v[8:11], v[170:173], v[200:203], v[8:11]
	v_mfma_f32_16x16x32_bf16 v[4:7], v[162:165], v[208:211], v[4:7]
	v_mfma_f32_16x16x32_bf16 v[0:3], v[170:173], v[208:211], v[0:3]
	s_waitcnt lgkmcnt(0)
	s_waitcnt vmcnt(6)
	s_barrier
	v_mfma_f32_16x16x32_bf16 v[60:63], v[150:153], v[188:191], v[60:63]
	ds_read_b128 v[184:187], v144
	v_lshl_add_u64 v[140:141], v[212:213], 0, s[78:79]
	v_mfma_f32_16x16x32_bf16 v[56:59], v[158:161], v[188:191], v[56:59]
	v_add_u32_e32 v154, s93, v142
	ds_read_b128 v[146:149], v154 offset:256
	s_mov_b32 m0, s35
	v_mfma_f32_16x16x32_bf16 v[52:55], v[150:153], v[196:199], v[52:55]
	ds_read_b128 v[154:157], v154 offset:2304
	s_nop 0
	v_mfma_f32_16x16x32_bf16 v[44:47], v[158:161], v[196:199], v[44:47]
	ds_read_b128 v[192:195], v144 offset:2048
	global_load_lds_dwordx4 v[140:141], off
	v_mfma_f32_16x16x32_bf16 v[36:39], v[150:153], v[204:207], v[36:39]
	ds_read_b128 v[200:203], v144 offset:4096
	v_lshl_add_u64 v[140:141], v[230:231], 0, s[78:79]
	v_mfma_f32_16x16x32_bf16 v[28:31], v[158:161], v[204:207], v[28:31]
	ds_read_b128 v[208:211], v144 offset:6144
	s_mov_b32 m0, s36
	v_mfma_f32_16x16x32_bf16 v[20:23], v[150:153], v[226:229], v[20:23]
	v_add_u32_e32 v170, s62, v142
	ds_read_b128 v[162:165], v170 offset:256
	s_nop 0
	v_mfma_f32_16x16x32_bf16 v[12:15], v[158:161], v[226:229], v[12:15]
	ds_read_b128 v[170:173], v170 offset:2304
	global_load_lds_dwordx4 v[140:141], off
	v_mfma_f32_16x16x32_bf16 v[48:51], v[166:169], v[188:191], v[48:51]
	v_mfma_f32_16x16x32_bf16 v[40:43], v[180:183], v[188:191], v[40:43]
	v_mfma_f32_16x16x32_bf16 v[32:35], v[166:169], v[196:199], v[32:35]
	v_mfma_f32_16x16x32_bf16 v[24:27], v[180:183], v[196:199], v[24:27]
	v_mfma_f32_16x16x32_bf16 v[16:19], v[166:169], v[204:207], v[16:19]
	v_mfma_f32_16x16x32_bf16 v[8:11], v[180:183], v[204:207], v[8:11]
	v_mfma_f32_16x16x32_bf16 v[4:7], v[166:169], v[226:229], v[4:7]
	v_mfma_f32_16x16x32_bf16 v[0:3], v[180:183], v[226:229], v[0:3]
	s_add_i32 s44, s44, 2
	s_add_u32 s18, s18, 0x100
	s_addc_u32 s19, s19, 0
	s_add_u32 s42, s42, 0x100
	s_addc_u32 s43, s43, 0
	s_cmpk_gt_u32 s44, 0x7d
	s_cbranch_scc0 .Lpg_g10_loop
	s_waitcnt lgkmcnt(0)
	s_and_b64 vcc, exec, s[8:9]
	s_cbranch_vccz .LBB0_1123
	s_nop 0
